# nt hint extended to all P2 epilogue stores (generic w_in path, transposed segments, channel DFT) and the position-DFT epilogue stores
# speedup vs baseline: 1.0797x; 1.0049x over previous
.LBB0_224:
	s_cmp_gt_i32 s6, 31
	s_cselect_b64 s[38:39], -1, 0
	s_cmp_lt_i32 s7, 2
	s_cselect_b64 s[42:43], -1, 0
	s_or_b64 s[42:43], s[38:39], s[42:43]
	s_cmp_lt_u32 s7, 4
	s_brev_b32 s11, 16
	s_cselect_b32 s11, s11, 0x10000000
	s_add_u32 s11, s20, s11
	s_addc_u32 s13, s21, 0
	s_lshl_b32 s7, s7, 8
	v_mov_b32_e32 v140, v148
	v_mov_b32_e32 v141, v149
	s_add_i32 s7, s7, s48
	s_lshl_b32 s44, s6, 2
	v_add_u32_e32 v144, s7, v140
	v_ashrrev_i32_e32 v145, 31, v144
	v_lshl_add_u32 v142, v141, 3, s49
	s_ashr_i32 s7, s6, 31
	v_lshlrev_b64 v[140:141], 15, v[144:145]
	s_lshl_b64 s[38:39], s[6:7], 9
	v_lshl_add_u64 v[140:141], s[24:25], 0, v[140:141]
	v_ashrrev_i32_e32 v143, 31, v142
	v_lshl_add_u64 v[140:141], v[140:141], 0, s[38:39]
	v_and_b32_e32 v145, 0x1ff, v144
	v_lshl_add_u64 v[146:147], v[142:143], 1, v[140:141]
	v_cvt_pk_bf16_f32 v152, v124, v125
	v_cvt_pk_bf16_f32 v153, v126, v127
	v_cvt_pk_bf16_f32 v154, v120, v121
	v_cvt_pk_bf16_f32 v155, v122, v123
	s_and_b64 vcc, exec, s[42:43]
	v_lshlrev_b64 v[140:141], 11, v[142:143]
	v_lshlrev_b32_e32 v192, 2, v145
	flat_store_dwordx4 v[146:147], v[152:155] nt
	s_cbranch_vccnz .LBB0_226
	s_or_b32 s6, s44, s88
	s_ashr_i32 s7, s6, 31
	s_lshl_b64 s[6:7], s[6:7], 19
	s_add_u32 s6, s11, s6
	s_addc_u32 s7, s13, s7
	v_lshl_add_u64 v[152:153], s[6:7], 0, v[140:141]
	v_lshl_add_u64 v[152:153], v[152:153], 0, v[192:193]
	global_store_dword v[152:153], v124, off nt
	global_store_dword v[152:153], v125, off offset:2048 nt
	v_add_co_u32_e32 v124, vcc, 0x1000, v152
	s_nop 1
	v_addc_co_u32_e32 v125, vcc, 0, v153, vcc
	global_store_dword v[124:125], v126, off nt
	global_store_dword v[124:125], v127, off offset:2048 nt
	v_add_co_u32_e32 v124, vcc, 0x2000, v152
	s_nop 1
	v_addc_co_u32_e32 v125, vcc, 0, v153, vcc
	global_store_dword v[124:125], v120, off nt
	global_store_dword v[124:125], v121, off offset:2048 nt
	v_add_co_u32_e32 v120, vcc, 0x3000, v152
	s_nop 1
	v_addc_co_u32_e32 v121, vcc, 0, v153, vcc
	global_store_dword v[120:121], v122, off nt
	global_store_dword v[120:121], v123, off offset:2048 nt
.LBB0_226:
	s_xor_b64 s[42:43], s[42:43], -1
	v_cvt_pk_bf16_f32 v120, v116, v117
	v_cvt_pk_bf16_f32 v121, v118, v119
	v_cvt_pk_bf16_f32 v122, v112, v113
	v_cvt_pk_bf16_f32 v123, v114, v115
	flat_store_dwordx4 v[146:147], v[120:123] offset:256 nt
	s_andn2_b64 vcc, exec, s[42:43]
	s_nop 0
	v_cndmask_b32_e64 v120, 0, 1, s[42:43]
	v_cmp_ne_u32_e64 s[6:7], 1, v120
	s_cbranch_vccnz .LBB0_228
	s_or_b32 s42, s44, s88
	s_ashr_i32 s43, s42, 31
	s_lshl_b64 s[42:43], s[42:43], 19
	s_add_u32 s42, s11, s42
	s_addc_u32 s43, s13, s43
	v_lshl_add_u64 v[120:121], s[42:43], 0, v[140:141]
	v_lshl_add_u64 v[120:121], v[120:121], 0, v[192:193]
	s_mov_b64 s[42:43], 0x40000
	v_lshl_add_u64 v[122:123], v[120:121], 0, s[42:43]
	s_mov_b32 s42, 0x40000
	v_add_co_u32_e32 v124, vcc, s42, v120
	s_nop 1
	v_addc_co_u32_e32 v125, vcc, 0, v121, vcc
	global_store_dword v[124:125], v116, off nt
	global_store_dword v[122:123], v117, off offset:2048 nt
	v_add_co_u32_e32 v116, vcc, 0x41000, v120
	s_nop 1
	v_addc_co_u32_e32 v117, vcc, 0, v121, vcc
	global_store_dword v[116:117], v118, off nt
	global_store_dword v[116:117], v119, off offset:2048 nt
	v_add_co_u32_e32 v116, vcc, 0x42000, v120
	s_nop 1
	v_addc_co_u32_e32 v117, vcc, 0, v121, vcc
	global_store_dword v[116:117], v112, off nt
	global_store_dword v[116:117], v113, off offset:2048 nt
	v_add_co_u32_e32 v112, vcc, 0x43000, v120
	s_nop 1
	v_addc_co_u32_e32 v113, vcc, 0, v121, vcc
	global_store_dword v[112:113], v114, off nt
	global_store_dword v[112:113], v115, off offset:2048 nt
.LBB0_228:
	v_add_u32_e32 v114, 16, v144
	v_ashrrev_i32_e32 v115, 31, v114
	v_lshlrev_b64 v[112:113], 15, v[114:115]
	v_lshl_add_u64 v[112:113], s[24:25], 0, v[112:113]
	v_lshl_add_u64 v[112:113], v[112:113], 0, s[38:39]
	v_and_b32_e32 v118, 0x1ff, v114
	v_lshl_add_u64 v[112:113], v[142:143], 1, v[112:113]
	v_cvt_pk_bf16_f32 v114, v108, v109
	v_cvt_pk_bf16_f32 v115, v110, v111
	v_cvt_pk_bf16_f32 v116, v104, v105
	v_cvt_pk_bf16_f32 v117, v106, v107
	s_and_b64 vcc, exec, s[6:7]
	v_lshlrev_b32_e32 v192, 2, v118
	flat_store_dwordx4 v[112:113], v[114:117] nt
	s_cbranch_vccnz .LBB0_230
	s_or_b32 s42, s44, s88
	s_ashr_i32 s43, s42, 31
	s_lshl_b64 s[42:43], s[42:43], 19
	s_add_u32 s42, s11, s42
	s_addc_u32 s43, s13, s43
	v_lshl_add_u64 v[114:115], s[42:43], 0, v[140:141]
	v_lshl_add_u64 v[114:115], v[114:115], 0, v[192:193]
	global_store_dword v[114:115], v108, off nt
	global_store_dword v[114:115], v109, off offset:2048 nt
	v_add_co_u32_e32 v108, vcc, 0x1000, v114
	s_nop 1
	v_addc_co_u32_e32 v109, vcc, 0, v115, vcc
	global_store_dword v[108:109], v110, off nt
	global_store_dword v[108:109], v111, off offset:2048 nt
	v_add_co_u32_e32 v108, vcc, 0x2000, v114
	s_nop 1
	v_addc_co_u32_e32 v109, vcc, 0, v115, vcc
	global_store_dword v[108:109], v104, off nt
	global_store_dword v[108:109], v105, off offset:2048 nt
	v_add_co_u32_e32 v104, vcc, 0x3000, v114
	s_nop 1
	v_addc_co_u32_e32 v105, vcc, 0, v115, vcc
	global_store_dword v[104:105], v106, off nt
	global_store_dword v[104:105], v107, off offset:2048 nt
.LBB0_230:
	v_cvt_pk_bf16_f32 v104, v100, v101
	v_cvt_pk_bf16_f32 v105, v102, v103
	v_cvt_pk_bf16_f32 v106, v96, v97
	v_cvt_pk_bf16_f32 v107, v98, v99
	s_and_b64 vcc, exec, s[6:7]
	flat_store_dwordx4 v[112:113], v[104:107] offset:256 nt
	s_cbranch_vccnz .LBB0_232
	s_or_b32 s42, s44, s88
	s_ashr_i32 s43, s42, 31
	s_lshl_b64 s[42:43], s[42:43], 19
	s_add_u32 s42, s11, s42
	s_addc_u32 s43, s13, s43
	v_lshl_add_u64 v[104:105], s[42:43], 0, v[140:141]
	v_lshl_add_u64 v[104:105], v[104:105], 0, v[192:193]
	s_mov_b64 s[42:43], 0x40000
	v_lshl_add_u64 v[106:107], v[104:105], 0, s[42:43]
	s_mov_b32 s42, 0x40000
	v_add_co_u32_e32 v108, vcc, s42, v104
	s_nop 1
	v_addc_co_u32_e32 v109, vcc, 0, v105, vcc
	global_store_dword v[108:109], v100, off nt
	global_store_dword v[106:107], v101, off offset:2048 nt
	v_add_co_u32_e32 v100, vcc, 0x41000, v104
	s_nop 1
	v_addc_co_u32_e32 v101, vcc, 0, v105, vcc
	global_store_dword v[100:101], v102, off nt
	global_store_dword v[100:101], v103, off offset:2048 nt
	v_add_co_u32_e32 v100, vcc, 0x42000, v104
	s_nop 1
	v_addc_co_u32_e32 v101, vcc, 0, v105, vcc
	global_store_dword v[100:101], v96, off nt
	global_store_dword v[100:101], v97, off offset:2048 nt
	v_add_co_u32_e32 v96, vcc, 0x43000, v104
	s_nop 1
	v_addc_co_u32_e32 v97, vcc, 0, v105, vcc
	global_store_dword v[96:97], v98, off nt
	global_store_dword v[96:97], v99, off offset:2048 nt
.LBB0_232:
	v_add_u32_e32 v98, 32, v144
	v_ashrrev_i32_e32 v99, 31, v98
	v_lshlrev_b64 v[96:97], 15, v[98:99]
	v_lshl_add_u64 v[96:97], s[24:25], 0, v[96:97]
	v_lshl_add_u64 v[96:97], v[96:97], 0, s[38:39]
	v_and_b32_e32 v102, 0x1ff, v98
	v_lshl_add_u64 v[96:97], v[142:143], 1, v[96:97]
	v_cvt_pk_bf16_f32 v98, v92, v93
	v_cvt_pk_bf16_f32 v99, v94, v95
	v_cvt_pk_bf16_f32 v100, v88, v89
	v_cvt_pk_bf16_f32 v101, v90, v91
	s_and_b64 vcc, exec, s[6:7]
	v_lshlrev_b32_e32 v192, 2, v102
	flat_store_dwordx4 v[96:97], v[98:101] nt
	s_cbranch_vccnz .LBB0_234
	s_or_b32 s42, s44, s88
	s_ashr_i32 s43, s42, 31
	s_lshl_b64 s[42:43], s[42:43], 19
	s_add_u32 s42, s11, s42
	s_addc_u32 s43, s13, s43
	v_lshl_add_u64 v[98:99], s[42:43], 0, v[140:141]
	v_lshl_add_u64 v[98:99], v[98:99], 0, v[192:193]
	global_store_dword v[98:99], v92, off nt
	global_store_dword v[98:99], v93, off offset:2048 nt
	v_add_co_u32_e32 v92, vcc, 0x1000, v98
	s_nop 1
	v_addc_co_u32_e32 v93, vcc, 0, v99, vcc
	global_store_dword v[92:93], v94, off nt
	global_store_dword v[92:93], v95, off offset:2048 nt
	v_add_co_u32_e32 v92, vcc, 0x2000, v98
	s_nop 1
	v_addc_co_u32_e32 v93, vcc, 0, v99, vcc
	global_store_dword v[92:93], v88, off nt
	global_store_dword v[92:93], v89, off offset:2048 nt
	v_add_co_u32_e32 v88, vcc, 0x3000, v98
	s_nop 1
	v_addc_co_u32_e32 v89, vcc, 0, v99, vcc
	global_store_dword v[88:89], v90, off nt
	global_store_dword v[88:89], v91, off offset:2048 nt
.LBB0_234:
	v_cvt_pk_bf16_f32 v88, v84, v85
	v_cvt_pk_bf16_f32 v89, v86, v87
	v_cvt_pk_bf16_f32 v90, v80, v81
	v_cvt_pk_bf16_f32 v91, v82, v83
	s_and_b64 vcc, exec, s[6:7]
	flat_store_dwordx4 v[96:97], v[88:91] offset:256 nt
	s_cbranch_vccnz .LBB0_236
	s_or_b32 s42, s44, s88
	s_ashr_i32 s43, s42, 31
	s_lshl_b64 s[42:43], s[42:43], 19
	s_add_u32 s42, s11, s42
	s_addc_u32 s43, s13, s43
	v_lshl_add_u64 v[88:89], s[42:43], 0, v[140:141]
	v_lshl_add_u64 v[88:89], v[88:89], 0, v[192:193]
	s_mov_b64 s[42:43], 0x40000
	v_lshl_add_u64 v[90:91], v[88:89], 0, s[42:43]
	s_mov_b32 s42, 0x40000
	v_add_co_u32_e32 v92, vcc, s42, v88
	s_nop 1
	v_addc_co_u32_e32 v93, vcc, 0, v89, vcc
	global_store_dword v[92:93], v84, off nt
	global_store_dword v[90:91], v85, off offset:2048 nt
	v_add_co_u32_e32 v84, vcc, 0x41000, v88
	s_nop 1
	v_addc_co_u32_e32 v85, vcc, 0, v89, vcc
	global_store_dword v[84:85], v86, off nt
	global_store_dword v[84:85], v87, off offset:2048 nt
	v_add_co_u32_e32 v84, vcc, 0x42000, v88
	s_nop 1
	v_addc_co_u32_e32 v85, vcc, 0, v89, vcc
	global_store_dword v[84:85], v80, off nt
	global_store_dword v[84:85], v81, off offset:2048 nt
	v_add_co_u32_e32 v80, vcc, 0x43000, v88
	s_nop 1
	v_addc_co_u32_e32 v81, vcc, 0, v89, vcc
	global_store_dword v[80:81], v82, off nt
	global_store_dword v[80:81], v83, off offset:2048 nt
.LBB0_236:
	v_add_u32_e32 v82, 48, v144
	v_ashrrev_i32_e32 v83, 31, v82
	v_lshlrev_b64 v[80:81], 15, v[82:83]
	v_lshl_add_u64 v[80:81], s[24:25], 0, v[80:81]
	v_lshl_add_u64 v[80:81], v[80:81], 0, s[38:39]
	v_and_b32_e32 v86, 0x1ff, v82
	v_lshl_add_u64 v[80:81], v[142:143], 1, v[80:81]
	v_cvt_pk_bf16_f32 v82, v76, v77
	v_cvt_pk_bf16_f32 v83, v78, v79
	v_cvt_pk_bf16_f32 v84, v72, v73
	v_cvt_pk_bf16_f32 v85, v74, v75
	s_and_b64 vcc, exec, s[6:7]
	v_lshlrev_b32_e32 v192, 2, v86
	flat_store_dwordx4 v[80:81], v[82:85] nt
	s_cbranch_vccnz .LBB0_238
	s_or_b32 s42, s44, s88
	s_ashr_i32 s43, s42, 31
	s_lshl_b64 s[42:43], s[42:43], 19
	s_add_u32 s42, s11, s42
	s_addc_u32 s43, s13, s43
	v_lshl_add_u64 v[82:83], s[42:43], 0, v[140:141]
	v_lshl_add_u64 v[82:83], v[82:83], 0, v[192:193]
	global_store_dword v[82:83], v76, off nt
	global_store_dword v[82:83], v77, off offset:2048 nt
	v_add_co_u32_e32 v76, vcc, 0x1000, v82
	s_nop 1
	v_addc_co_u32_e32 v77, vcc, 0, v83, vcc
	global_store_dword v[76:77], v78, off nt
	global_store_dword v[76:77], v79, off offset:2048 nt
	v_add_co_u32_e32 v76, vcc, 0x2000, v82
	s_nop 1
	v_addc_co_u32_e32 v77, vcc, 0, v83, vcc
	global_store_dword v[76:77], v72, off nt
	global_store_dword v[76:77], v73, off offset:2048 nt
	v_add_co_u32_e32 v72, vcc, 0x3000, v82
	s_nop 1
	v_addc_co_u32_e32 v73, vcc, 0, v83, vcc
	global_store_dword v[72:73], v74, off nt
	global_store_dword v[72:73], v75, off offset:2048 nt
.LBB0_238:
	v_cvt_pk_bf16_f32 v72, v68, v69
	v_cvt_pk_bf16_f32 v73, v70, v71
	v_cvt_pk_bf16_f32 v74, v64, v65
	v_cvt_pk_bf16_f32 v75, v66, v67
	s_and_b64 vcc, exec, s[6:7]
	flat_store_dwordx4 v[80:81], v[72:75] offset:256 nt
	s_cbranch_vccnz .LBB0_240
	s_or_b32 s42, s44, s88
	s_ashr_i32 s43, s42, 31
	s_lshl_b64 s[42:43], s[42:43], 19
	s_add_u32 s42, s11, s42
	s_addc_u32 s43, s13, s43
	v_lshl_add_u64 v[72:73], s[42:43], 0, v[140:141]
	v_lshl_add_u64 v[72:73], v[72:73], 0, v[192:193]
	s_mov_b64 s[42:43], 0x40000
	v_lshl_add_u64 v[74:75], v[72:73], 0, s[42:43]
	s_mov_b32 s42, 0x40000
	v_add_co_u32_e32 v76, vcc, s42, v72
	s_nop 1
	v_addc_co_u32_e32 v77, vcc, 0, v73, vcc
	global_store_dword v[76:77], v68, off nt
	global_store_dword v[74:75], v69, off offset:2048 nt
	v_add_co_u32_e32 v68, vcc, 0x41000, v72
	s_nop 1
	v_addc_co_u32_e32 v69, vcc, 0, v73, vcc
	global_store_dword v[68:69], v70, off nt
	global_store_dword v[68:69], v71, off offset:2048 nt
	v_add_co_u32_e32 v68, vcc, 0x42000, v72
	s_nop 1
	v_addc_co_u32_e32 v69, vcc, 0, v73, vcc
	global_store_dword v[68:69], v64, off nt
	global_store_dword v[68:69], v65, off offset:2048 nt
	v_add_co_u32_e32 v64, vcc, 0x43000, v72
	s_nop 1
	v_addc_co_u32_e32 v65, vcc, 0, v73, vcc
	global_store_dword v[64:65], v66, off nt
	global_store_dword v[64:65], v67, off offset:2048 nt
.LBB0_240:
	v_add_u32_e32 v66, 0x80, v144
	v_ashrrev_i32_e32 v67, 31, v66
	v_lshlrev_b64 v[64:65], 15, v[66:67]
	v_lshl_add_u64 v[64:65], s[24:25], 0, v[64:65]
	v_lshl_add_u64 v[64:65], v[64:65], 0, s[38:39]
	v_and_b32_e32 v70, 0x1ff, v66
	v_lshl_add_u64 v[64:65], v[142:143], 1, v[64:65]
	v_cvt_pk_bf16_f32 v66, v60, v61
	v_cvt_pk_bf16_f32 v67, v62, v63
	v_cvt_pk_bf16_f32 v68, v56, v57
	v_cvt_pk_bf16_f32 v69, v58, v59
	s_and_b64 vcc, exec, s[6:7]
	v_lshlrev_b32_e32 v192, 2, v70
	flat_store_dwordx4 v[64:65], v[66:69] nt
	s_cbranch_vccnz .LBB0_242
	s_or_b32 s42, s44, s88
	s_ashr_i32 s43, s42, 31
	s_lshl_b64 s[42:43], s[42:43], 19
	s_add_u32 s42, s11, s42
	s_addc_u32 s43, s13, s43
	v_lshl_add_u64 v[66:67], s[42:43], 0, v[140:141]
	v_lshl_add_u64 v[66:67], v[66:67], 0, v[192:193]
	global_store_dword v[66:67], v60, off nt
	global_store_dword v[66:67], v61, off offset:2048 nt
	v_add_co_u32_e32 v60, vcc, 0x1000, v66
	s_nop 1
	v_addc_co_u32_e32 v61, vcc, 0, v67, vcc
	global_store_dword v[60:61], v62, off nt
	global_store_dword v[60:61], v63, off offset:2048 nt
	v_add_co_u32_e32 v60, vcc, 0x2000, v66
	s_nop 1
	v_addc_co_u32_e32 v61, vcc, 0, v67, vcc
	global_store_dword v[60:61], v56, off nt
	global_store_dword v[60:61], v57, off offset:2048 nt
	v_add_co_u32_e32 v56, vcc, 0x3000, v66
	s_nop 1
	v_addc_co_u32_e32 v57, vcc, 0, v67, vcc
	global_store_dword v[56:57], v58, off nt
	global_store_dword v[56:57], v59, off offset:2048 nt
.LBB0_242:
	v_cvt_pk_bf16_f32 v56, v52, v53
	v_cvt_pk_bf16_f32 v57, v54, v55
	v_cvt_pk_bf16_f32 v58, v48, v49
	v_cvt_pk_bf16_f32 v59, v50, v51
	s_and_b64 vcc, exec, s[6:7]
	flat_store_dwordx4 v[64:65], v[56:59] offset:256 nt
	s_cbranch_vccnz .LBB0_244
	s_or_b32 s42, s44, s88
	s_ashr_i32 s43, s42, 31
	s_lshl_b64 s[42:43], s[42:43], 19
	s_add_u32 s42, s11, s42
	s_addc_u32 s43, s13, s43
	v_lshl_add_u64 v[56:57], s[42:43], 0, v[140:141]
	v_lshl_add_u64 v[56:57], v[56:57], 0, v[192:193]
	s_mov_b64 s[42:43], 0x40000
	v_lshl_add_u64 v[58:59], v[56:57], 0, s[42:43]
	s_mov_b32 s42, 0x40000
	v_add_co_u32_e32 v60, vcc, s42, v56
	s_nop 1
	v_addc_co_u32_e32 v61, vcc, 0, v57, vcc
	global_store_dword v[60:61], v52, off nt
	global_store_dword v[58:59], v53, off offset:2048 nt
	v_add_co_u32_e32 v52, vcc, 0x41000, v56
	s_nop 1
	v_addc_co_u32_e32 v53, vcc, 0, v57, vcc
	global_store_dword v[52:53], v54, off nt
	global_store_dword v[52:53], v55, off offset:2048 nt
	v_add_co_u32_e32 v52, vcc, 0x42000, v56
	s_nop 1
	v_addc_co_u32_e32 v53, vcc, 0, v57, vcc
	global_store_dword v[52:53], v48, off nt
	global_store_dword v[52:53], v49, off offset:2048 nt
	v_add_co_u32_e32 v48, vcc, 0x43000, v56
	s_nop 1
	v_addc_co_u32_e32 v49, vcc, 0, v57, vcc
	global_store_dword v[48:49], v50, off nt
	global_store_dword v[48:49], v51, off offset:2048 nt
.LBB0_244:
	v_add_u32_e32 v50, 0x90, v144
	v_ashrrev_i32_e32 v51, 31, v50
	v_lshlrev_b64 v[48:49], 15, v[50:51]
	v_lshl_add_u64 v[48:49], s[24:25], 0, v[48:49]
	v_lshl_add_u64 v[48:49], v[48:49], 0, s[38:39]
	v_and_b32_e32 v54, 0x1ff, v50
	v_lshl_add_u64 v[48:49], v[142:143], 1, v[48:49]
	v_cvt_pk_bf16_f32 v50, v44, v45
	v_cvt_pk_bf16_f32 v51, v46, v47
	v_cvt_pk_bf16_f32 v52, v40, v41
	v_cvt_pk_bf16_f32 v53, v42, v43
	s_and_b64 vcc, exec, s[6:7]
	v_lshlrev_b32_e32 v192, 2, v54
	flat_store_dwordx4 v[48:49], v[50:53] nt
	s_cbranch_vccnz .LBB0_246
	s_or_b32 s42, s44, s88
	s_ashr_i32 s43, s42, 31
	s_lshl_b64 s[42:43], s[42:43], 19
	s_add_u32 s42, s11, s42
	s_addc_u32 s43, s13, s43
	v_lshl_add_u64 v[50:51], s[42:43], 0, v[140:141]
	v_lshl_add_u64 v[50:51], v[50:51], 0, v[192:193]
	global_store_dword v[50:51], v44, off nt
	global_store_dword v[50:51], v45, off offset:2048 nt
	v_add_co_u32_e32 v44, vcc, 0x1000, v50
	s_nop 1
	v_addc_co_u32_e32 v45, vcc, 0, v51, vcc
	global_store_dword v[44:45], v46, off nt
	global_store_dword v[44:45], v47, off offset:2048 nt
	v_add_co_u32_e32 v44, vcc, 0x2000, v50
	s_nop 1
	v_addc_co_u32_e32 v45, vcc, 0, v51, vcc
	global_store_dword v[44:45], v40, off nt
	global_store_dword v[44:45], v41, off offset:2048 nt
	v_add_co_u32_e32 v40, vcc, 0x3000, v50
	s_nop 1
	v_addc_co_u32_e32 v41, vcc, 0, v51, vcc
	global_store_dword v[40:41], v42, off nt
	global_store_dword v[40:41], v43, off offset:2048 nt
.LBB0_246:
	v_cvt_pk_bf16_f32 v40, v36, v37
	v_cvt_pk_bf16_f32 v41, v38, v39
	v_cvt_pk_bf16_f32 v42, v32, v33
	v_cvt_pk_bf16_f32 v43, v34, v35
	s_and_b64 vcc, exec, s[6:7]
	flat_store_dwordx4 v[48:49], v[40:43] offset:256 nt
	s_cbranch_vccnz .LBB0_248
	s_or_b32 s42, s44, s88
	s_ashr_i32 s43, s42, 31
	s_lshl_b64 s[42:43], s[42:43], 19
	s_add_u32 s42, s11, s42
	s_addc_u32 s43, s13, s43
	v_lshl_add_u64 v[40:41], s[42:43], 0, v[140:141]
	v_lshl_add_u64 v[40:41], v[40:41], 0, v[192:193]
	s_mov_b64 s[42:43], 0x40000
	v_lshl_add_u64 v[42:43], v[40:41], 0, s[42:43]
	s_mov_b32 s42, 0x40000
	v_add_co_u32_e32 v44, vcc, s42, v40
	s_nop 1
	v_addc_co_u32_e32 v45, vcc, 0, v41, vcc
	global_store_dword v[44:45], v36, off nt
	global_store_dword v[42:43], v37, off offset:2048 nt
	v_add_co_u32_e32 v36, vcc, 0x41000, v40
	s_nop 1
	v_addc_co_u32_e32 v37, vcc, 0, v41, vcc
	global_store_dword v[36:37], v38, off nt
	global_store_dword v[36:37], v39, off offset:2048 nt
	v_add_co_u32_e32 v36, vcc, 0x42000, v40
	s_nop 1
	v_addc_co_u32_e32 v37, vcc, 0, v41, vcc
	global_store_dword v[36:37], v32, off nt
	global_store_dword v[36:37], v33, off offset:2048 nt
	v_add_co_u32_e32 v32, vcc, 0x43000, v40
	s_nop 1
	v_addc_co_u32_e32 v33, vcc, 0, v41, vcc
	global_store_dword v[32:33], v34, off nt
	global_store_dword v[32:33], v35, off offset:2048 nt
.LBB0_248:
	v_add_u32_e32 v34, 0xa0, v144
	v_ashrrev_i32_e32 v35, 31, v34
	v_lshlrev_b64 v[32:33], 15, v[34:35]
	v_lshl_add_u64 v[32:33], s[24:25], 0, v[32:33]
	v_lshl_add_u64 v[32:33], v[32:33], 0, s[38:39]
	v_and_b32_e32 v38, 0x1ff, v34
	v_lshl_add_u64 v[32:33], v[142:143], 1, v[32:33]
	v_cvt_pk_bf16_f32 v34, v28, v29
	v_cvt_pk_bf16_f32 v35, v30, v31
	v_cvt_pk_bf16_f32 v36, v24, v25
	v_cvt_pk_bf16_f32 v37, v26, v27
	s_and_b64 vcc, exec, s[6:7]
	v_lshlrev_b32_e32 v192, 2, v38
	flat_store_dwordx4 v[32:33], v[34:37] nt
	s_cbranch_vccnz .LBB0_250
	s_or_b32 s42, s44, s88
	s_ashr_i32 s43, s42, 31
	s_lshl_b64 s[42:43], s[42:43], 19
	s_add_u32 s42, s11, s42
	s_addc_u32 s43, s13, s43
	v_lshl_add_u64 v[34:35], s[42:43], 0, v[140:141]
	v_lshl_add_u64 v[34:35], v[34:35], 0, v[192:193]
	global_store_dword v[34:35], v28, off nt
	global_store_dword v[34:35], v29, off offset:2048 nt
	v_add_co_u32_e32 v28, vcc, 0x1000, v34
	s_nop 1
	v_addc_co_u32_e32 v29, vcc, 0, v35, vcc
	global_store_dword v[28:29], v30, off nt
	global_store_dword v[28:29], v31, off offset:2048 nt
	v_add_co_u32_e32 v28, vcc, 0x2000, v34
	s_nop 1
	v_addc_co_u32_e32 v29, vcc, 0, v35, vcc
	global_store_dword v[28:29], v24, off nt
	global_store_dword v[28:29], v25, off offset:2048 nt
	v_add_co_u32_e32 v24, vcc, 0x3000, v34
	s_nop 1
	v_addc_co_u32_e32 v25, vcc, 0, v35, vcc
	global_store_dword v[24:25], v26, off nt
	global_store_dword v[24:25], v27, off offset:2048 nt
.LBB0_250:
	v_cvt_pk_bf16_f32 v24, v20, v21
	v_cvt_pk_bf16_f32 v25, v22, v23
	v_cvt_pk_bf16_f32 v26, v16, v17
	v_cvt_pk_bf16_f32 v27, v18, v19
	s_and_b64 vcc, exec, s[6:7]
	flat_store_dwordx4 v[32:33], v[24:27] offset:256 nt
	s_cbranch_vccnz .LBB0_252
	s_or_b32 s42, s44, s88
	s_ashr_i32 s43, s42, 31
	s_lshl_b64 s[42:43], s[42:43], 19
	s_add_u32 s42, s11, s42
	s_addc_u32 s43, s13, s43
	v_lshl_add_u64 v[24:25], s[42:43], 0, v[140:141]
	v_lshl_add_u64 v[24:25], v[24:25], 0, v[192:193]
	s_mov_b64 s[42:43], 0x40000
	v_lshl_add_u64 v[26:27], v[24:25], 0, s[42:43]
	s_mov_b32 s42, 0x40000
	v_add_co_u32_e32 v28, vcc, s42, v24
	s_nop 1
	v_addc_co_u32_e32 v29, vcc, 0, v25, vcc
	global_store_dword v[28:29], v20, off nt
	global_store_dword v[26:27], v21, off offset:2048 nt
	v_add_co_u32_e32 v20, vcc, 0x41000, v24
	s_nop 1
	v_addc_co_u32_e32 v21, vcc, 0, v25, vcc
	global_store_dword v[20:21], v22, off nt
	global_store_dword v[20:21], v23, off offset:2048 nt
	v_add_co_u32_e32 v20, vcc, 0x42000, v24
	s_nop 1
	v_addc_co_u32_e32 v21, vcc, 0, v25, vcc
	global_store_dword v[20:21], v16, off nt
	global_store_dword v[20:21], v17, off offset:2048 nt
	v_add_co_u32_e32 v16, vcc, 0x43000, v24
	s_nop 1
	v_addc_co_u32_e32 v17, vcc, 0, v25, vcc
	global_store_dword v[16:17], v18, off nt
	global_store_dword v[16:17], v19, off offset:2048 nt
.LBB0_252:
	v_add_u32_e32 v18, 0xb0, v144
	v_ashrrev_i32_e32 v19, 31, v18
	v_lshlrev_b64 v[16:17], 15, v[18:19]
	v_lshl_add_u64 v[16:17], s[24:25], 0, v[16:17]
	v_lshl_add_u64 v[16:17], v[16:17], 0, s[38:39]
	v_and_b32_e32 v22, 0x1ff, v18
	v_lshl_add_u64 v[16:17], v[142:143], 1, v[16:17]
	v_cvt_pk_bf16_f32 v18, v12, v13
	v_cvt_pk_bf16_f32 v19, v14, v15
	v_cvt_pk_bf16_f32 v20, v8, v9
	v_cvt_pk_bf16_f32 v21, v10, v11
	s_and_b64 vcc, exec, s[6:7]
	v_lshlrev_b32_e32 v192, 2, v22
	flat_store_dwordx4 v[16:17], v[18:21] nt
	s_cbranch_vccnz .LBB0_254
	s_or_b32 s38, s44, s88
	s_ashr_i32 s39, s38, 31
	s_lshl_b64 s[38:39], s[38:39], 19
	s_add_u32 s38, s11, s38
	s_addc_u32 s39, s13, s39
	v_lshl_add_u64 v[18:19], s[38:39], 0, v[140:141]
	v_lshl_add_u64 v[18:19], v[18:19], 0, v[192:193]
	global_store_dword v[18:19], v12, off nt
	global_store_dword v[18:19], v13, off offset:2048 nt
	v_add_co_u32_e32 v12, vcc, 0x1000, v18
	s_nop 1
	v_addc_co_u32_e32 v13, vcc, 0, v19, vcc
	global_store_dword v[12:13], v14, off nt
	global_store_dword v[12:13], v15, off offset:2048 nt
	v_add_co_u32_e32 v12, vcc, 0x2000, v18
	s_nop 1
	v_addc_co_u32_e32 v13, vcc, 0, v19, vcc
	global_store_dword v[12:13], v8, off nt
	global_store_dword v[12:13], v9, off offset:2048 nt
	v_add_co_u32_e32 v8, vcc, 0x3000, v18
	s_nop 1
	v_addc_co_u32_e32 v9, vcc, 0, v19, vcc
	global_store_dword v[8:9], v10, off nt
	global_store_dword v[8:9], v11, off offset:2048 nt
.LBB0_254:
	v_cvt_pk_bf16_f32 v8, v4, v5
	v_cvt_pk_bf16_f32 v9, v6, v7
	v_cvt_pk_bf16_f32 v10, v0, v1
	v_cvt_pk_bf16_f32 v11, v2, v3
	s_and_b64 vcc, exec, s[6:7]
	flat_store_dwordx4 v[16:17], v[8:11] offset:256 nt
	s_cbranch_vccnz .LBB0_256
	s_or_b32 s6, s44, s88
	s_ashr_i32 s7, s6, 31
	s_lshl_b64 s[6:7], s[6:7], 19
	s_add_u32 s6, s11, s6
	s_addc_u32 s7, s13, s7
	v_lshl_add_u64 v[8:9], s[6:7], 0, v[140:141]
	v_lshl_add_u64 v[8:9], v[8:9], 0, v[192:193]
	s_mov_b64 s[6:7], 0x40000
	v_lshl_add_u64 v[10:11], v[8:9], 0, s[6:7]
	s_mov_b32 s6, 0x40000
	v_add_co_u32_e32 v12, vcc, s6, v8
	s_nop 1
	v_addc_co_u32_e32 v13, vcc, 0, v9, vcc
	global_store_dword v[12:13], v4, off nt
	global_store_dword v[10:11], v5, off offset:2048 nt
	v_add_co_u32_e32 v4, vcc, 0x41000, v8
	s_nop 1
	v_addc_co_u32_e32 v5, vcc, 0, v9, vcc
	global_store_dword v[4:5], v6, off nt
	global_store_dword v[4:5], v7, off offset:2048 nt
	v_add_co_u32_e32 v4, vcc, 0x42000, v8
	s_nop 1
	v_addc_co_u32_e32 v5, vcc, 0, v9, vcc
	global_store_dword v[4:5], v0, off nt
	global_store_dword v[4:5], v1, off offset:2048 nt
	v_add_co_u32_e32 v0, vcc, 0x43000, v8
	s_nop 1
	v_addc_co_u32_e32 v1, vcc, 0, v9, vcc
	global_store_dword v[0:1], v2, off nt
	global_store_dword v[0:1], v3, off offset:2048 nt

.LBB0_285:
	s_lshl_b64 s[30:31], s[40:41], 1
	s_add_u32 s9, s42, s30
	s_addc_u32 s11, s43, s31
	s_add_u32 s30, s9, s66
	v_lshlrev_b32_e32 v138, 3, v138
	v_add_u32_e32 v142, s58, v139
	s_addc_u32 s31, s11, 0
	v_ashrrev_i32_e32 v139, 31, v138
	v_lshl_add_u64 v[138:139], v[138:139], 1, s[30:31]
	v_mad_i64_i32 v[140:141], s[30:31], s38, v142, 0
	v_cvt_pk_bf16_f32 v108, v108, v109
	v_cvt_pk_bf16_f32 v109, v110, v111
	v_cvt_pk_bf16_f32 v110, v104, v105
	v_add_u32_e32 v104, 16, v142
	v_lshl_add_u64 v[140:141], v[140:141], 1, v[138:139]
	v_cvt_pk_bf16_f32 v111, v106, v107
	v_mad_i64_i32 v[104:105], s[30:31], s38, v104, 0
	v_cvt_pk_bf16_f32 v92, v92, v93
	v_cvt_pk_bf16_f32 v93, v94, v95
	v_cvt_pk_bf16_f32 v94, v88, v89
	v_add_u32_e32 v88, 32, v142
	v_cvt_pk_bf16_f32 v124, v124, v125
	v_cvt_pk_bf16_f32 v125, v126, v127
	v_cvt_pk_bf16_f32 v126, v120, v121
	v_cvt_pk_bf16_f32 v127, v122, v123
	flat_store_dwordx4 v[140:141], v[108:111] offset:256 nt
	v_cvt_pk_bf16_f32 v95, v90, v91
	v_mad_i64_i32 v[88:89], s[30:31], s38, v88, 0
	v_lshl_add_u64 v[108:109], v[104:105], 1, v[138:139]
	v_cvt_pk_bf16_f32 v76, v76, v77
	v_cvt_pk_bf16_f32 v77, v78, v79
	v_cvt_pk_bf16_f32 v78, v72, v73
	v_add_u32_e32 v72, 48, v142
	v_cvt_pk_bf16_f32 v68, v68, v69
	v_cvt_pk_bf16_f32 v69, v70, v71
	v_cvt_pk_bf16_f32 v70, v64, v65
	v_add_u32_e32 v64, 0x80, v142
	flat_store_dwordx4 v[140:141], v[124:127] nt
	v_cvt_pk_bf16_f32 v104, v116, v117
	v_cvt_pk_bf16_f32 v105, v118, v119
	v_cvt_pk_bf16_f32 v106, v112, v113
	v_cvt_pk_bf16_f32 v107, v114, v115
	flat_store_dwordx4 v[108:109], v[92:95] offset:256 nt
	v_cvt_pk_bf16_f32 v79, v74, v75
	v_mad_i64_i32 v[72:73], s[30:31], s38, v72, 0
	v_lshl_add_u64 v[92:93], v[88:89], 1, v[138:139]
	v_mad_i64_i32 v[64:65], s[30:31], s38, v64, 0
	v_cvt_pk_bf16_f32 v44, v44, v45
	v_cvt_pk_bf16_f32 v45, v46, v47
	v_cvt_pk_bf16_f32 v46, v40, v41
	v_add_u32_e32 v40, 0x90, v142
	flat_store_dwordx4 v[108:109], v[104:107] nt
	v_cvt_pk_bf16_f32 v88, v100, v101
	v_cvt_pk_bf16_f32 v89, v102, v103
	v_cvt_pk_bf16_f32 v90, v96, v97
	v_cvt_pk_bf16_f32 v91, v98, v99
	flat_store_dwordx4 v[92:93], v[76:79] offset:256 nt
	v_cvt_pk_bf16_f32 v74, v80, v81
	v_cvt_pk_bf16_f32 v75, v82, v83
	v_lshl_add_u64 v[76:77], v[72:73], 1, v[138:139]
	v_cvt_pk_bf16_f32 v72, v84, v85
	v_cvt_pk_bf16_f32 v73, v86, v87
	v_cvt_pk_bf16_f32 v71, v66, v67
	v_lshl_add_u64 v[64:65], v[64:65], 1, v[138:139]
	v_cvt_pk_bf16_f32 v47, v42, v43
	v_mad_i64_i32 v[40:41], s[30:31], s38, v40, 0
	v_cvt_pk_bf16_f32 v28, v28, v29
	v_cvt_pk_bf16_f32 v29, v30, v31
	v_cvt_pk_bf16_f32 v30, v24, v25
	v_add_u32_e32 v24, 0xa0, v142
	flat_store_dwordx4 v[92:93], v[88:91] nt
	flat_store_dwordx4 v[76:77], v[72:75] nt
	flat_store_dwordx4 v[76:77], v[68:71] offset:256 nt
	v_cvt_pk_bf16_f32 v60, v60, v61
	v_cvt_pk_bf16_f32 v61, v62, v63
	v_cvt_pk_bf16_f32 v62, v56, v57
	v_cvt_pk_bf16_f32 v63, v58, v59
	flat_store_dwordx4 v[64:65], v[44:47] offset:256 nt
	v_cvt_pk_bf16_f32 v31, v26, v27
	v_mad_i64_i32 v[24:25], s[30:31], s38, v24, 0
	v_lshl_add_u64 v[44:45], v[40:41], 1, v[138:139]
	v_cvt_pk_bf16_f32 v12, v12, v13
	v_cvt_pk_bf16_f32 v13, v14, v15
	v_cvt_pk_bf16_f32 v14, v8, v9
	v_add_u32_e32 v8, 0xb0, v142
	flat_store_dwordx4 v[64:65], v[60:63] nt
	v_cvt_pk_bf16_f32 v40, v52, v53
	v_cvt_pk_bf16_f32 v41, v54, v55
	v_cvt_pk_bf16_f32 v42, v48, v49
	v_cvt_pk_bf16_f32 v43, v50, v51
	flat_store_dwordx4 v[44:45], v[28:31] offset:256 nt
	v_cvt_pk_bf16_f32 v15, v10, v11
	v_mad_i64_i32 v[8:9], s[30:31], s38, v8, 0
	v_lshl_add_u64 v[28:29], v[24:25], 1, v[138:139]
	flat_store_dwordx4 v[44:45], v[40:43] nt
	v_cvt_pk_bf16_f32 v24, v36, v37
	v_cvt_pk_bf16_f32 v25, v38, v39
	v_cvt_pk_bf16_f32 v26, v32, v33
	v_cvt_pk_bf16_f32 v27, v34, v35
	flat_store_dwordx4 v[28:29], v[12:15] offset:256 nt
	v_cvt_pk_bf16_f32 v10, v16, v17
	v_cvt_pk_bf16_f32 v11, v18, v19
	v_lshl_add_u64 v[12:13], v[8:9], 1, v[138:139]
	v_cvt_pk_bf16_f32 v8, v20, v21
	v_cvt_pk_bf16_f32 v9, v22, v23
	v_cvt_pk_bf16_f32 v4, v4, v5
	v_cvt_pk_bf16_f32 v5, v6, v7
	v_cvt_pk_bf16_f32 v6, v0, v1
	v_cvt_pk_bf16_f32 v7, v2, v3
	s_and_b64 vcc, exec, s[6:7]
	s_mov_b64 s[6:7], -1
	flat_store_dwordx4 v[28:29], v[24:27] nt
	flat_store_dwordx4 v[12:13], v[8:11] nt
	flat_store_dwordx4 v[12:13], v[4:7] offset:256 nt
	s_cbranch_vccnz .LBB0_272
	s_andn2_b64 vcc, exec, s[0:1]
	s_cbranch_vccnz .LBB0_271
	s_barrier
	s_branch .LBB0_271

.LBB0_319:
	s_cmp_eq_u32 s33, 3
	s_cselect_b64 s[54:55], -1, 0
	s_and_b64 s[54:55], s[14:15], s[54:55]
	s_cmp_eq_u32 s33, 6
	s_cselect_b64 s[66:67], -1, 0
	s_and_b64 s[14:15], s[14:15], s[66:67]
	s_and_b64 s[14:15], s[14:15], exec
	s_cselect_b32 s9, s29, 0
	s_cselect_b32 s11, s36, 0
	s_and_b64 s[14:15], s[54:55], exec
	s_cselect_b32 s67, s28, s11
	s_cselect_b32 s66, s97, s9
	s_cmp_lg_u64 s[66:67], 0
	s_cselect_b64 s[14:15], -1, 0
	s_lshl_b32 s8, s8, 10
	s_lshl_b32 s73, s10, 2
	s_and_b32 s8, s8, 0x400
	s_add_u32 s54, s66, s8
	s_addc_u32 s55, s67, 0
	v_lshlrev_b64 v[136:137], 11, v[160:161]
	s_cmp_eq_u64 s[66:67], 0
	v_lshl_add_u64 v[174:175], s[54:55], 0, v[136:137]
	s_cbranch_scc1 .LBB0_321
	s_or_b32 s8, s73, s88
	s_ashr_i32 s9, s8, 31
	s_lshl_b64 s[8:9], s[8:9], 19
	v_lshl_add_u64 v[136:137], v[174:175], 0, s[8:9]
	v_lshl_add_u64 v[136:137], v[156:157], 2, v[136:137]
	global_store_dwordx4 v[136:137], v[124:127], off nt
	global_store_dwordx4 v[136:137], v[120:123], off offset:16 nt

.LBB0_333:
	v_cndmask_b32_e64 v124, 0, 1, s[14:15]
	v_cvt_pk_bf16_f32 v120, v136, v137
	v_cvt_pk_bf16_f32 v121, v138, v139
	v_cvt_pk_bf16_f32 v122, v140, v141
	v_cvt_pk_bf16_f32 v123, v142, v143
	v_cmp_ne_u32_e64 s[12:13], 1, v124
	s_andn2_b64 vcc, exec, s[14:15]
	flat_store_dwordx4 v[164:165], v[120:123] nt
	s_cbranch_vccnz .LBB0_335
	s_or_b32 s14, s73, s88
	s_ashr_i32 s15, s14, 31
	s_lshl_b64 s[14:15], s[14:15], 19
	v_lshl_add_u64 v[120:121], v[174:175], 0, s[14:15]
	v_lshl_add_u64 v[120:121], v[156:157], 2, v[120:121]
	global_store_dwordx4 v[120:121], v[116:119], off offset:512 nt
	global_store_dwordx4 v[120:121], v[112:115], off offset:528 nt

.LBB0_347:
	s_lshl_b32 s40, s16, 1
	v_cndmask_b32_e64 v118, 0, 1, s[56:57]
	v_cvt_pk_bf16_f32 v112, v120, v121
	v_cvt_pk_bf16_f32 v113, v122, v123
	v_cvt_pk_bf16_f32 v114, v124, v125
	v_cvt_pk_bf16_f32 v115, v126, v127
	v_lshl_add_u64 v[116:117], v[164:165], 0, s[40:41]
	v_cmp_ne_u32_e64 s[16:17], 1, v118
	s_andn2_b64 vcc, exec, s[56:57]
	flat_store_dwordx4 v[116:117], v[112:115] nt
	s_cbranch_vccnz .LBB0_349
	s_nop 0
	v_add_u32_e32 v112, 0x400, v192
	v_mov_b32_e32 v113, v193
	v_lshl_add_u64 v[128:129], v[112:113], 1, s[30:31]
	s_mov_b64 s[56:57], 0
	s_branch .LBB0_350

.LBB0_355:
	s_or_b32 s56, s73, s88
	s_ashr_i32 s57, s56, 31
	s_lshl_b64 s[56:57], s[56:57], 19
	v_lshl_add_u64 v[120:121], v[138:139], 0, s[56:57]
	v_lshl_add_u64 v[120:121], v[156:157], 2, v[120:121]
	global_store_dwordx4 v[120:121], v[108:111], off nt
	global_store_dwordx4 v[120:121], v[104:107], off offset:16 nt

.LBB0_368:
	v_cvt_pk_bf16_f32 v104, v120, v121
	v_cvt_pk_bf16_f32 v105, v122, v123
	v_cvt_pk_bf16_f32 v106, v124, v125
	v_cvt_pk_bf16_f32 v107, v126, v127
	s_and_b64 vcc, exec, s[12:13]
	flat_store_dwordx4 v[128:129], v[104:107] nt
	s_cbranch_vccnz .LBB0_370
	s_or_b32 s56, s73, s88
	s_ashr_i32 s57, s56, 31
	s_lshl_b64 s[56:57], s[56:57], 19
	v_lshl_add_u64 v[104:105], v[138:139], 0, s[56:57]
	v_lshl_add_u64 v[104:105], v[156:157], 2, v[104:105]
	global_store_dwordx4 v[104:105], v[100:103], off offset:512 nt
	global_store_dwordx4 v[104:105], v[96:99], off offset:528 nt

.LBB0_382:
	v_cvt_pk_bf16_f32 v96, v104, v105
	v_cvt_pk_bf16_f32 v97, v106, v107
	v_cvt_pk_bf16_f32 v98, v108, v109
	v_cvt_pk_bf16_f32 v99, v110, v111
	v_lshl_add_u64 v[100:101], v[128:129], 0, s[40:41]
	s_and_b64 vcc, exec, s[16:17]
	flat_store_dwordx4 v[100:101], v[96:99] nt
	s_cbranch_vccnz .LBB0_384
	s_nop 0
	v_add_u32_e32 v96, 0x800, v192
	v_mov_b32_e32 v97, v193
	v_lshl_add_u64 v[112:113], v[96:97], 1, s[30:31]
	s_mov_b64 s[56:57], 0
	s_branch .LBB0_385

.LBB0_390:
	s_or_b32 s56, s73, s88
	s_ashr_i32 s57, s56, 31
	s_lshl_b64 s[56:57], s[56:57], 19
	v_lshl_add_u64 v[104:105], v[122:123], 0, s[56:57]
	v_lshl_add_u64 v[104:105], v[156:157], 2, v[104:105]
	global_store_dwordx4 v[104:105], v[92:95], off nt
	global_store_dwordx4 v[104:105], v[88:91], off offset:16 nt

.LBB0_403:
	v_cvt_pk_bf16_f32 v88, v104, v105
	v_cvt_pk_bf16_f32 v89, v106, v107
	v_cvt_pk_bf16_f32 v90, v108, v109
	v_cvt_pk_bf16_f32 v91, v110, v111
	s_and_b64 vcc, exec, s[12:13]
	flat_store_dwordx4 v[112:113], v[88:91] nt
	s_cbranch_vccnz .LBB0_405
	s_or_b32 s56, s73, s88
	s_ashr_i32 s57, s56, 31
	s_lshl_b64 s[56:57], s[56:57], 19
	v_lshl_add_u64 v[88:89], v[122:123], 0, s[56:57]
	v_lshl_add_u64 v[88:89], v[156:157], 2, v[88:89]
	global_store_dwordx4 v[88:89], v[84:87], off offset:512 nt
	global_store_dwordx4 v[88:89], v[80:83], off offset:528 nt

.LBB0_417:
	v_cvt_pk_bf16_f32 v80, v88, v89
	v_cvt_pk_bf16_f32 v81, v90, v91
	v_cvt_pk_bf16_f32 v82, v92, v93
	v_cvt_pk_bf16_f32 v83, v94, v95
	v_lshl_add_u64 v[84:85], v[112:113], 0, s[40:41]
	s_and_b64 vcc, exec, s[16:17]
	flat_store_dwordx4 v[84:85], v[80:83] nt
	s_cbranch_vccnz .LBB0_419
	v_add_u32_e32 v192, 0xc00, v192
	v_lshl_add_u64 v[96:97], v[192:193], 1, s[30:31]
	s_mov_b64 s[56:57], 0
	s_branch .LBB0_420

.LBB0_425:
	s_or_b32 s56, s73, s88
	s_ashr_i32 s57, s56, 31
	s_lshl_b64 s[56:57], s[56:57], 19
	v_lshl_add_u64 v[88:89], v[106:107], 0, s[56:57]
	v_lshl_add_u64 v[88:89], v[156:157], 2, v[88:89]
	global_store_dwordx4 v[88:89], v[76:79], off nt
	global_store_dwordx4 v[88:89], v[72:75], off offset:16 nt

.LBB0_438:
	v_cvt_pk_bf16_f32 v72, v88, v89
	v_cvt_pk_bf16_f32 v73, v90, v91
	v_cvt_pk_bf16_f32 v74, v92, v93
	v_cvt_pk_bf16_f32 v75, v94, v95
	s_and_b64 vcc, exec, s[12:13]
	flat_store_dwordx4 v[96:97], v[72:75] nt
	s_cbranch_vccnz .LBB0_440
	s_or_b32 s56, s73, s88
	s_ashr_i32 s57, s56, 31
	s_lshl_b64 s[56:57], s[56:57], 19
	v_lshl_add_u64 v[72:73], v[106:107], 0, s[56:57]
	v_lshl_add_u64 v[72:73], v[156:157], 2, v[72:73]
	global_store_dwordx4 v[72:73], v[68:71], off offset:512 nt
	global_store_dwordx4 v[72:73], v[64:67], off offset:528 nt

.LBB0_452:
	v_cvt_pk_bf16_f32 v64, v72, v73
	v_cvt_pk_bf16_f32 v65, v74, v75
	v_cvt_pk_bf16_f32 v66, v76, v77
	v_cvt_pk_bf16_f32 v67, v78, v79
	v_lshl_add_u64 v[68:69], v[96:97], 0, s[40:41]
	s_and_b64 vcc, exec, s[16:17]
	v_add_u32_e32 v192, s68, v180
	flat_store_dwordx4 v[68:69], v[64:67] nt
	s_cbranch_vccnz .LBB0_454
	v_lshl_add_u64 v[80:81], v[192:193], 1, s[30:31]
	s_mov_b64 s[56:57], 0
	s_branch .LBB0_455

.LBB0_460:
	s_or_b32 s56, s73, s88
	s_ashr_i32 s57, s56, 31
	s_lshl_b64 s[56:57], s[56:57], 19
	v_lshl_add_u64 v[72:73], v[90:91], 0, s[56:57]
	v_lshl_add_u64 v[72:73], v[156:157], 2, v[72:73]
	global_store_dwordx4 v[72:73], v[60:63], off nt
	global_store_dwordx4 v[72:73], v[56:59], off offset:16 nt

.LBB0_473:
	v_cvt_pk_bf16_f32 v56, v72, v73
	v_cvt_pk_bf16_f32 v57, v74, v75
	v_cvt_pk_bf16_f32 v58, v76, v77
	v_cvt_pk_bf16_f32 v59, v78, v79
	s_and_b64 vcc, exec, s[12:13]
	flat_store_dwordx4 v[80:81], v[56:59] nt
	s_cbranch_vccnz .LBB0_475
	s_or_b32 s56, s73, s88
	s_ashr_i32 s57, s56, 31
	s_lshl_b64 s[56:57], s[56:57], 19
	v_lshl_add_u64 v[56:57], v[90:91], 0, s[56:57]
	v_lshl_add_u64 v[56:57], v[156:157], 2, v[56:57]
	global_store_dwordx4 v[56:57], v[52:55], off offset:512 nt
	global_store_dwordx4 v[56:57], v[48:51], off offset:528 nt

.LBB0_487:
	v_cvt_pk_bf16_f32 v48, v56, v57
	v_cvt_pk_bf16_f32 v49, v58, v59
	v_cvt_pk_bf16_f32 v50, v60, v61
	v_cvt_pk_bf16_f32 v51, v62, v63
	v_lshl_add_u64 v[52:53], v[80:81], 0, s[40:41]
	s_and_b64 vcc, exec, s[16:17]
	flat_store_dwordx4 v[52:53], v[48:51] nt
	s_cbranch_vccnz .LBB0_489
	s_nop 0
	v_add_u32_e32 v48, 0x400, v192
	v_mov_b32_e32 v49, v193
	v_lshl_add_u64 v[64:65], v[48:49], 1, s[30:31]
	s_mov_b64 s[56:57], 0
	s_branch .LBB0_490

.LBB0_495:
	s_or_b32 s56, s73, s88
	s_ashr_i32 s57, s56, 31
	s_lshl_b64 s[56:57], s[56:57], 19
	v_lshl_add_u64 v[56:57], v[74:75], 0, s[56:57]
	v_lshl_add_u64 v[56:57], v[156:157], 2, v[56:57]
	global_store_dwordx4 v[56:57], v[44:47], off nt
	global_store_dwordx4 v[56:57], v[40:43], off offset:16 nt

.LBB0_508:
	v_cvt_pk_bf16_f32 v40, v56, v57
	v_cvt_pk_bf16_f32 v41, v58, v59
	v_cvt_pk_bf16_f32 v42, v60, v61
	v_cvt_pk_bf16_f32 v43, v62, v63
	s_and_b64 vcc, exec, s[12:13]
	flat_store_dwordx4 v[64:65], v[40:43] nt
	s_cbranch_vccnz .LBB0_510
	s_or_b32 s56, s73, s88
	s_ashr_i32 s57, s56, 31
	s_lshl_b64 s[56:57], s[56:57], 19
	v_lshl_add_u64 v[40:41], v[74:75], 0, s[56:57]
	v_lshl_add_u64 v[40:41], v[156:157], 2, v[40:41]
	global_store_dwordx4 v[40:41], v[36:39], off offset:512 nt
	global_store_dwordx4 v[40:41], v[32:35], off offset:528 nt

.LBB0_522:
	v_cvt_pk_bf16_f32 v32, v40, v41
	v_cvt_pk_bf16_f32 v33, v42, v43
	v_cvt_pk_bf16_f32 v34, v44, v45
	v_cvt_pk_bf16_f32 v35, v46, v47
	v_lshl_add_u64 v[36:37], v[64:65], 0, s[40:41]
	s_and_b64 vcc, exec, s[16:17]
	flat_store_dwordx4 v[36:37], v[32:35] nt
	s_cbranch_vccnz .LBB0_524
	s_nop 0
	v_add_u32_e32 v32, 0x800, v192
	v_mov_b32_e32 v33, v193
	v_lshl_add_u64 v[48:49], v[32:33], 1, s[30:31]
	s_mov_b64 s[56:57], 0
	s_branch .LBB0_525

.LBB0_530:
	s_or_b32 s56, s73, s88
	s_ashr_i32 s57, s56, 31
	s_lshl_b64 s[56:57], s[56:57], 19
	v_lshl_add_u64 v[40:41], v[58:59], 0, s[56:57]
	v_lshl_add_u64 v[40:41], v[156:157], 2, v[40:41]
	global_store_dwordx4 v[40:41], v[28:31], off nt
	global_store_dwordx4 v[40:41], v[24:27], off offset:16 nt

.LBB0_543:
	v_cvt_pk_bf16_f32 v24, v40, v41
	v_cvt_pk_bf16_f32 v25, v42, v43
	v_cvt_pk_bf16_f32 v26, v44, v45
	v_cvt_pk_bf16_f32 v27, v46, v47
	s_and_b64 vcc, exec, s[12:13]
	flat_store_dwordx4 v[48:49], v[24:27] nt
	s_cbranch_vccnz .LBB0_545
	s_or_b32 s56, s73, s88
	s_ashr_i32 s57, s56, 31
	s_lshl_b64 s[56:57], s[56:57], 19
	v_lshl_add_u64 v[24:25], v[58:59], 0, s[56:57]
	v_lshl_add_u64 v[24:25], v[156:157], 2, v[24:25]
	global_store_dwordx4 v[24:25], v[20:23], off offset:512 nt
	global_store_dwordx4 v[24:25], v[16:19], off offset:528 nt

.LBB0_557:
	v_cvt_pk_bf16_f32 v16, v24, v25
	v_cvt_pk_bf16_f32 v17, v26, v27
	v_cvt_pk_bf16_f32 v18, v28, v29
	v_cvt_pk_bf16_f32 v19, v30, v31
	v_lshl_add_u64 v[20:21], v[48:49], 0, s[40:41]
	s_and_b64 vcc, exec, s[16:17]
	flat_store_dwordx4 v[20:21], v[16:19] nt
	s_cbranch_vccnz .LBB0_559
	v_add_u32_e32 v192, 0xc00, v192
	v_lshl_add_u64 v[32:33], v[192:193], 1, s[30:31]
	s_mov_b64 s[16:17], 0
	s_branch .LBB0_560

.LBB0_565:
	s_or_b32 s16, s73, s88
	s_ashr_i32 s17, s16, 31
	s_lshl_b64 s[16:17], s[16:17], 19
	v_lshl_add_u64 v[24:25], v[42:43], 0, s[16:17]
	v_lshl_add_u64 v[24:25], v[156:157], 2, v[24:25]
	global_store_dwordx4 v[24:25], v[12:15], off nt
	global_store_dwordx4 v[24:25], v[8:11], off offset:16 nt

.LBB0_578:
	v_cvt_pk_bf16_f32 v8, v24, v25
	v_cvt_pk_bf16_f32 v9, v26, v27
	v_cvt_pk_bf16_f32 v10, v28, v29
	v_cvt_pk_bf16_f32 v11, v30, v31
	s_and_b64 vcc, exec, s[12:13]
	flat_store_dwordx4 v[32:33], v[8:11] nt
	s_cbranch_vccnz .LBB0_580
	s_or_b32 s12, s73, s88
	s_ashr_i32 s13, s12, 31
	s_lshl_b64 s[12:13], s[12:13], 19
	v_lshl_add_u64 v[8:9], v[42:43], 0, s[12:13]
	v_lshl_add_u64 v[8:9], v[156:157], 2, v[8:9]
	global_store_dwordx4 v[8:9], v[4:7], off offset:512 nt
	global_store_dwordx4 v[8:9], v[0:3], off offset:528 nt

.LBB0_592:
	v_cvt_pk_bf16_f32 v0, v8, v9
	v_cvt_pk_bf16_f32 v1, v10, v11
	v_cvt_pk_bf16_f32 v2, v12, v13
	v_cvt_pk_bf16_f32 v3, v14, v15
	v_lshl_add_u64 v[4:5], v[32:33], 0, s[40:41]
	s_andn2_b64 vcc, exec, s[42:43]
	s_mov_b64 s[8:9], -1
	flat_store_dwordx4 v[4:5], v[0:3] nt
	s_cbranch_vccnz .LBB0_295

.LBB0_653:
	s_lshl_b32 s13, s18, 8
	v_mov_b32_e32 v128, v164
	v_mov_b32_e32 v129, v165
	s_or_b32 s13, s13, s43
	s_lshl_b32 s11, s20, 8
	v_lshl_add_u32 v192, v129, 3, s13
	s_bfe_i32 s13, s20, 0x180000
	s_mul_hi_i32 s19, s13, 0x280000
	s_mul_i32 s13, s13, 0x280000
	s_add_u32 s13, s39, s13
	s_addc_u32 s20, s40, s19
	s_ashr_i32 s19, s18, 31
	s_lshl_b64 s[18:19], s[18:19], 17
	s_add_u32 s18, s13, s18
	v_lshlrev_b32_e32 v130, 3, v128
	s_addc_u32 s19, s20, s19
	v_lshl_add_u32 v169, v129, 7, v130
	s_add_i32 s11, s11, s42
	v_add_u32_e32 v168, s11, v128
	v_add_u32_e32 v128, s46, v169
	v_mov_b32_e32 v129, v193
	v_lshl_add_u64 v[128:129], v[128:129], 1, s[18:19]
	flat_load_dwordx4 v[170:173], v[128:129]
	v_add_u32_e32 v128, s47, v169
	v_mov_b32_e32 v129, v193
	v_lshl_add_u64 v[128:129], v[128:129], 1, s[18:19]
	flat_load_dwordx4 v[174:177], v[128:129]
	v_add_u32_e32 v128, s48, v169
	v_mov_b32_e32 v129, v193
	v_lshl_add_u64 v[128:129], v[128:129], 1, s[18:19]
	flat_load_dwordx4 v[148:151], v[128:129]
	v_add_u32_e32 v128, s49, v169
	v_mov_b32_e32 v129, v193
	v_lshl_add_u64 v[128:129], v[128:129], 1, s[18:19]
	flat_load_dwordx4 v[144:147], v[128:129]
	v_add_u32_e32 v128, s50, v169
	v_mov_b32_e32 v129, v193
	v_lshl_add_u64 v[128:129], v[128:129], 1, s[18:19]
	flat_load_dwordx4 v[140:143], v[128:129]
	v_add_u32_e32 v128, s51, v169
	v_mov_b32_e32 v129, v193
	v_lshl_add_u64 v[128:129], v[128:129], 1, s[18:19]
	flat_load_dwordx4 v[136:139], v[128:129]
	v_add_u32_e32 v128, s52, v169
	v_mov_b32_e32 v129, v193
	v_lshl_add_u64 v[128:129], v[128:129], 1, s[18:19]
	flat_load_dwordx4 v[132:135], v[128:129]
	v_add_u32_e32 v128, s53, v169
	v_mov_b32_e32 v129, v193
	v_lshl_add_u64 v[128:129], v[128:129], 1, s[18:19]
	flat_load_dwordx4 v[128:131], v[128:129]
	s_movk_i32 s11, 0x1400
	s_andn2_b64 vcc, exec, s[16:17]
	s_waitcnt vmcnt(0) lgkmcnt(0)
	v_lshlrev_b32_e32 v178, 16, v170
	v_and_b32_e32 v179, 0xffff0000, v170
	v_lshlrev_b32_e32 v170, 16, v171
	v_and_b32_e32 v171, 0xffff0000, v171
	v_pk_mul_f32 v[124:125], v[124:125], v[178:179]
	v_pk_mul_f32 v[126:127], v[126:127], v[170:171]
	v_cvt_pk_bf16_f32 v124, v124, v125
	v_cvt_pk_bf16_f32 v125, v126, v127
	v_lshlrev_b32_e32 v126, 16, v172
	v_and_b32_e32 v127, 0xffff0000, v172
	v_pk_mul_f32 v[120:121], v[120:121], v[126:127]
	s_nop 0
	v_cvt_pk_bf16_f32 v126, v120, v121
	v_lshlrev_b32_e32 v120, 16, v173
	v_and_b32_e32 v121, 0xffff0000, v173
	v_pk_mul_f32 v[120:121], v[122:123], v[120:121]
	v_lshlrev_b64 v[122:123], 1, v[192:193]
	v_cvt_pk_bf16_f32 v127, v120, v121
	v_mov_b64_e32 v[120:121], s[6:7]
	v_mad_u64_u32 v[170:171], s[22:23], v168, s11, v[120:121]
	v_lshl_add_u64 v[170:171], v[170:171], 0, v[122:123]
	flat_store_dwordx4 v[170:171], v[124:127] offset:3072 nt
	v_add_u32_e32 v192, s54, v169
	s_nop 0
	v_lshlrev_b32_e32 v124, 16, v174
	v_and_b32_e32 v125, 0xffff0000, v174
	v_pk_mul_f32 v[116:117], v[116:117], v[124:125]
	v_lshlrev_b32_e32 v124, 16, v175
	v_and_b32_e32 v125, 0xffff0000, v175
	v_pk_mul_f32 v[118:119], v[118:119], v[124:125]
	v_cvt_pk_bf16_f32 v116, v116, v117
	v_cvt_pk_bf16_f32 v117, v118, v119
	v_lshlrev_b32_e32 v118, 16, v176
	v_and_b32_e32 v119, 0xffff0000, v176
	v_pk_mul_f32 v[112:113], v[112:113], v[118:119]
	s_nop 0
	v_cvt_pk_bf16_f32 v118, v112, v113
	v_lshlrev_b32_e32 v112, 16, v177
	v_and_b32_e32 v113, 0xffff0000, v177
	v_pk_mul_f32 v[112:113], v[114:115], v[112:113]
	v_add_u32_e32 v114, 16, v168
	v_cvt_pk_bf16_f32 v119, v112, v113
	v_lshlrev_b32_e32 v112, 16, v148
	v_and_b32_e32 v113, 0xffff0000, v148
	v_pk_mul_f32 v[108:109], v[108:109], v[112:113]
	v_lshlrev_b32_e32 v112, 16, v149
	v_and_b32_e32 v113, 0xffff0000, v149
	v_pk_mul_f32 v[110:111], v[110:111], v[112:113]
	v_cvt_pk_bf16_f32 v108, v108, v109
	v_cvt_pk_bf16_f32 v109, v110, v111
	v_lshlrev_b32_e32 v110, 16, v150
	v_and_b32_e32 v111, 0xffff0000, v150
	v_pk_mul_f32 v[104:105], v[104:105], v[110:111]
	flat_store_dwordx4 v[170:171], v[116:119] offset:3328 nt
	v_cvt_pk_bf16_f32 v110, v104, v105
	v_lshlrev_b32_e32 v104, 16, v151
	v_and_b32_e32 v105, 0xffff0000, v151
	v_pk_mul_f32 v[104:105], v[106:107], v[104:105]
	v_lshlrev_b32_e32 v106, 16, v144
	v_and_b32_e32 v107, 0xffff0000, v144
	v_pk_mul_f32 v[100:101], v[100:101], v[106:107]
	v_lshlrev_b32_e32 v106, 16, v145
	v_and_b32_e32 v107, 0xffff0000, v145
	v_pk_mul_f32 v[102:103], v[102:103], v[106:107]
	v_cvt_pk_bf16_f32 v100, v100, v101
	v_cvt_pk_bf16_f32 v101, v102, v103
	v_lshlrev_b32_e32 v102, 16, v146
	v_and_b32_e32 v103, 0xffff0000, v146
	v_pk_mul_f32 v[92:93], v[92:93], v[102:103]
	v_cvt_pk_bf16_f32 v111, v104, v105
	v_cvt_pk_bf16_f32 v102, v92, v93
	v_lshlrev_b32_e32 v92, 16, v147
	v_and_b32_e32 v93, 0xffff0000, v147
	v_pk_mul_f32 v[92:93], v[94:95], v[92:93]
	v_lshlrev_b32_e32 v94, 16, v141
	v_cvt_pk_bf16_f32 v103, v92, v93
	v_lshlrev_b32_e32 v92, 16, v140
	v_and_b32_e32 v93, 0xffff0000, v140
	v_and_b32_e32 v95, 0xffff0000, v141
	v_pk_mul_f32 v[92:93], v[96:97], v[92:93]
	v_pk_mul_f32 v[94:95], v[98:99], v[94:95]
	v_cvt_pk_bf16_f32 v92, v92, v93
	v_cvt_pk_bf16_f32 v93, v94, v95
	v_lshlrev_b32_e32 v94, 16, v142
	v_and_b32_e32 v95, 0xffff0000, v142
	v_pk_mul_f32 v[88:89], v[88:89], v[94:95]
	v_mad_u64_u32 v[104:105], s[22:23], v114, s11, v[120:121]
	v_cvt_pk_bf16_f32 v94, v88, v89
	v_lshlrev_b32_e32 v88, 16, v143
	v_and_b32_e32 v89, 0xffff0000, v143
	v_pk_mul_f32 v[88:89], v[90:91], v[88:89]
	v_lshlrev_b32_e32 v90, 16, v136
	v_and_b32_e32 v91, 0xffff0000, v136
	v_pk_mul_f32 v[84:85], v[84:85], v[90:91]
	v_lshlrev_b32_e32 v90, 16, v137
	v_and_b32_e32 v91, 0xffff0000, v137
	v_pk_mul_f32 v[86:87], v[86:87], v[90:91]
	v_cvt_pk_bf16_f32 v84, v84, v85
	v_cvt_pk_bf16_f32 v85, v86, v87
	v_lshlrev_b32_e32 v86, 16, v138
	v_and_b32_e32 v87, 0xffff0000, v138
	v_pk_mul_f32 v[76:77], v[76:77], v[86:87]
	v_lshl_add_u64 v[104:105], v[104:105], 0, v[122:123]
	v_cvt_pk_bf16_f32 v86, v76, v77
	v_lshlrev_b32_e32 v76, 16, v139
	v_and_b32_e32 v77, 0xffff0000, v139
	v_pk_mul_f32 v[76:77], v[78:79], v[76:77]
	v_lshlrev_b32_e32 v78, 16, v133
	v_cvt_pk_bf16_f32 v87, v76, v77
	v_lshlrev_b32_e32 v76, 16, v132
	v_and_b32_e32 v77, 0xffff0000, v132
	v_and_b32_e32 v79, 0xffff0000, v133
	v_pk_mul_f32 v[76:77], v[80:81], v[76:77]
	v_pk_mul_f32 v[78:79], v[82:83], v[78:79]
	v_cvt_pk_bf16_f32 v76, v76, v77
	v_cvt_pk_bf16_f32 v77, v78, v79
	v_lshlrev_b32_e32 v78, 16, v134
	v_and_b32_e32 v79, 0xffff0000, v134
	v_pk_mul_f32 v[72:73], v[72:73], v[78:79]
	flat_store_dwordx4 v[104:105], v[100:103] offset:3328 nt
	v_cvt_pk_bf16_f32 v78, v72, v73
	v_lshlrev_b32_e32 v72, 16, v135
	v_and_b32_e32 v73, 0xffff0000, v135
	v_pk_mul_f32 v[72:73], v[74:75], v[72:73]
	v_lshlrev_b32_e32 v74, 16, v128
	v_and_b32_e32 v75, 0xffff0000, v128
	v_pk_mul_f32 v[68:69], v[68:69], v[74:75]
	v_lshlrev_b32_e32 v74, 16, v129
	v_and_b32_e32 v75, 0xffff0000, v129
	v_add_u32_e32 v100, 32, v168
	v_pk_mul_f32 v[70:71], v[70:71], v[74:75]
	v_cvt_pk_bf16_f32 v95, v88, v89
	v_mad_u64_u32 v[88:89], s[22:23], v100, s11, v[120:121]
	v_cvt_pk_bf16_f32 v68, v68, v69
	v_cvt_pk_bf16_f32 v69, v70, v71
	v_lshlrev_b32_e32 v70, 16, v130
	v_and_b32_e32 v71, 0xffff0000, v130
	v_lshl_add_u64 v[88:89], v[88:89], 0, v[122:123]
	v_pk_mul_f32 v[64:65], v[64:65], v[70:71]
	flat_store_dwordx4 v[88:89], v[84:87] offset:3328 nt
	v_cvt_pk_bf16_f32 v70, v64, v65
	v_lshlrev_b32_e32 v64, 16, v131
	v_add_u32_e32 v84, 48, v168
	v_and_b32_e32 v65, 0xffff0000, v131
	v_cvt_pk_bf16_f32 v79, v72, v73
	v_mad_u64_u32 v[72:73], s[22:23], v84, s11, v[120:121]
	v_pk_mul_f32 v[64:65], v[66:67], v[64:65]
	v_lshl_add_u64 v[72:73], v[72:73], 0, v[122:123]
	v_cvt_pk_bf16_f32 v71, v64, v65
	flat_store_dwordx4 v[104:105], v[108:111] offset:3072 nt
	flat_store_dwordx4 v[88:89], v[92:95] offset:3072 nt
	flat_store_dwordx4 v[72:73], v[76:79] offset:3072 nt
	flat_store_dwordx4 v[72:73], v[68:71] offset:3328 nt
	v_lshl_add_u64 v[64:65], v[192:193], 1, s[18:19]
	flat_load_dwordx4 v[68:71], v[64:65]
	v_add_u32_e32 v192, s55, v169
	v_lshl_add_u64 v[64:65], v[192:193], 1, s[18:19]
	flat_load_dwordx4 v[72:75], v[64:65]
	v_add_u32_e32 v192, s56, v169
	v_lshl_add_u64 v[64:65], v[192:193], 1, s[18:19]
	flat_load_dwordx4 v[76:79], v[64:65]
	v_add_u32_e32 v192, s57, v169
	v_lshl_add_u64 v[64:65], v[192:193], 1, s[18:19]
	flat_load_dwordx4 v[80:83], v[64:65]
	v_add_u32_e32 v192, s58, v169
	v_lshl_add_u64 v[64:65], v[192:193], 1, s[18:19]
	flat_load_dwordx4 v[84:87], v[64:65]
	v_add_u32_e32 v192, s59, v169
	v_lshl_add_u64 v[64:65], v[192:193], 1, s[18:19]
	flat_load_dwordx4 v[88:91], v[64:65]
	v_add_u32_e32 v192, s60, v169
	v_lshl_add_u64 v[64:65], v[192:193], 1, s[18:19]
	flat_load_dwordx4 v[92:95], v[64:65]
	v_add_u32_e32 v192, s61, v169
	v_lshl_add_u64 v[64:65], v[192:193], 1, s[18:19]
	flat_load_dwordx4 v[64:67], v[64:65]
	v_add_u32_e32 v98, 0x80, v168
	s_waitcnt vmcnt(0) lgkmcnt(0)
	v_lshlrev_b32_e32 v96, 16, v68
	v_and_b32_e32 v97, 0xffff0000, v68
	v_lshlrev_b32_e32 v68, 16, v69
	v_and_b32_e32 v69, 0xffff0000, v69
	v_pk_mul_f32 v[60:61], v[60:61], v[96:97]
	v_pk_mul_f32 v[62:63], v[62:63], v[68:69]
	v_cvt_pk_bf16_f32 v60, v60, v61
	v_cvt_pk_bf16_f32 v61, v62, v63
	v_lshlrev_b32_e32 v62, 16, v70
	v_and_b32_e32 v63, 0xffff0000, v70
	v_pk_mul_f32 v[56:57], v[56:57], v[62:63]
	s_nop 0
	v_cvt_pk_bf16_f32 v62, v56, v57
	v_lshlrev_b32_e32 v56, 16, v71
	v_and_b32_e32 v57, 0xffff0000, v71
	v_pk_mul_f32 v[56:57], v[58:59], v[56:57]
	v_lshlrev_b32_e32 v58, 16, v72
	v_and_b32_e32 v59, 0xffff0000, v72
	v_pk_mul_f32 v[52:53], v[52:53], v[58:59]
	v_lshlrev_b32_e32 v58, 16, v73
	v_and_b32_e32 v59, 0xffff0000, v73
	v_pk_mul_f32 v[54:55], v[54:55], v[58:59]
	v_cvt_pk_bf16_f32 v52, v52, v53
	v_cvt_pk_bf16_f32 v53, v54, v55
	v_lshlrev_b32_e32 v54, 16, v74
	v_and_b32_e32 v55, 0xffff0000, v74
	v_pk_mul_f32 v[44:45], v[44:45], v[54:55]
	v_cvt_pk_bf16_f32 v63, v56, v57
	v_cvt_pk_bf16_f32 v54, v44, v45
	v_lshlrev_b32_e32 v44, 16, v75
	v_and_b32_e32 v45, 0xffff0000, v75
	v_pk_mul_f32 v[44:45], v[46:47], v[44:45]
	v_lshlrev_b32_e32 v46, 16, v77
	v_cvt_pk_bf16_f32 v55, v44, v45
	v_lshlrev_b32_e32 v44, 16, v76
	v_and_b32_e32 v45, 0xffff0000, v76
	v_and_b32_e32 v47, 0xffff0000, v77
	v_pk_mul_f32 v[44:45], v[48:49], v[44:45]
	v_pk_mul_f32 v[46:47], v[50:51], v[46:47]
	v_cvt_pk_bf16_f32 v44, v44, v45
	v_cvt_pk_bf16_f32 v45, v46, v47
	v_lshlrev_b32_e32 v46, 16, v78
	v_and_b32_e32 v47, 0xffff0000, v78
	v_pk_mul_f32 v[40:41], v[40:41], v[46:47]
	v_mad_u64_u32 v[56:57], s[18:19], v98, s11, v[120:121]
	v_cvt_pk_bf16_f32 v46, v40, v41
	v_lshlrev_b32_e32 v40, 16, v79
	v_and_b32_e32 v41, 0xffff0000, v79
	v_pk_mul_f32 v[40:41], v[42:43], v[40:41]
	v_lshlrev_b32_e32 v42, 16, v80
	v_and_b32_e32 v43, 0xffff0000, v80
	v_pk_mul_f32 v[36:37], v[36:37], v[42:43]
	v_lshlrev_b32_e32 v42, 16, v81
	v_and_b32_e32 v43, 0xffff0000, v81
	v_pk_mul_f32 v[38:39], v[38:39], v[42:43]
	v_cvt_pk_bf16_f32 v36, v36, v37
	v_cvt_pk_bf16_f32 v37, v38, v39
	v_lshlrev_b32_e32 v38, 16, v82
	v_and_b32_e32 v39, 0xffff0000, v82
	v_pk_mul_f32 v[28:29], v[28:29], v[38:39]
	v_lshl_add_u64 v[56:57], v[56:57], 0, v[122:123]
	v_cvt_pk_bf16_f32 v38, v28, v29
	v_lshlrev_b32_e32 v28, 16, v83
	v_and_b32_e32 v29, 0xffff0000, v83
	v_pk_mul_f32 v[28:29], v[30:31], v[28:29]
	v_lshlrev_b32_e32 v30, 16, v85
	v_cvt_pk_bf16_f32 v39, v28, v29
	v_lshlrev_b32_e32 v28, 16, v84
	v_and_b32_e32 v29, 0xffff0000, v84
	v_and_b32_e32 v31, 0xffff0000, v85
	v_pk_mul_f32 v[28:29], v[32:33], v[28:29]
	v_pk_mul_f32 v[30:31], v[34:35], v[30:31]
	v_cvt_pk_bf16_f32 v28, v28, v29
	v_cvt_pk_bf16_f32 v29, v30, v31
	v_lshlrev_b32_e32 v30, 16, v86
	v_and_b32_e32 v31, 0xffff0000, v86
	v_pk_mul_f32 v[24:25], v[24:25], v[30:31]
	flat_store_dwordx4 v[56:57], v[52:55] offset:3328 nt
	v_cvt_pk_bf16_f32 v30, v24, v25
	v_lshlrev_b32_e32 v24, 16, v87
	v_and_b32_e32 v25, 0xffff0000, v87
	v_pk_mul_f32 v[24:25], v[26:27], v[24:25]
	v_lshlrev_b32_e32 v26, 16, v88
	v_and_b32_e32 v27, 0xffff0000, v88
	v_pk_mul_f32 v[20:21], v[20:21], v[26:27]
	v_lshlrev_b32_e32 v26, 16, v89
	v_and_b32_e32 v27, 0xffff0000, v89
	v_pk_mul_f32 v[22:23], v[22:23], v[26:27]
	v_cvt_pk_bf16_f32 v20, v20, v21
	v_cvt_pk_bf16_f32 v21, v22, v23
	v_lshlrev_b32_e32 v22, 16, v90
	v_and_b32_e32 v23, 0xffff0000, v90
	v_pk_mul_f32 v[12:13], v[12:13], v[22:23]
	v_add_u32_e32 v52, 0x90, v168
	v_cvt_pk_bf16_f32 v22, v12, v13
	v_lshlrev_b32_e32 v12, 16, v91
	v_and_b32_e32 v13, 0xffff0000, v91
	v_pk_mul_f32 v[12:13], v[14:15], v[12:13]
	v_lshlrev_b32_e32 v14, 16, v93
	v_cvt_pk_bf16_f32 v23, v12, v13
	v_lshlrev_b32_e32 v12, 16, v92
	v_and_b32_e32 v13, 0xffff0000, v92
	v_and_b32_e32 v15, 0xffff0000, v93
	v_pk_mul_f32 v[12:13], v[16:17], v[12:13]
	v_pk_mul_f32 v[14:15], v[18:19], v[14:15]
	v_cvt_pk_bf16_f32 v12, v12, v13
	v_cvt_pk_bf16_f32 v13, v14, v15
	v_lshlrev_b32_e32 v14, 16, v94
	v_and_b32_e32 v15, 0xffff0000, v94
	v_pk_mul_f32 v[8:9], v[8:9], v[14:15]
	v_cvt_pk_bf16_f32 v47, v40, v41
	v_cvt_pk_bf16_f32 v14, v8, v9
	v_lshlrev_b32_e32 v8, 16, v95
	v_and_b32_e32 v9, 0xffff0000, v95
	v_mad_u64_u32 v[40:41], s[18:19], v52, s11, v[120:121]
	v_pk_mul_f32 v[8:9], v[10:11], v[8:9]
	v_lshlrev_b32_e32 v10, 16, v64
	v_and_b32_e32 v11, 0xffff0000, v64
	v_lshl_add_u64 v[40:41], v[40:41], 0, v[122:123]
	v_pk_mul_f32 v[4:5], v[4:5], v[10:11]
	v_lshlrev_b32_e32 v10, 16, v65
	v_and_b32_e32 v11, 0xffff0000, v65
	flat_store_dwordx4 v[40:41], v[36:39] offset:3328 nt
	v_pk_mul_f32 v[6:7], v[6:7], v[10:11]
	v_cvt_pk_bf16_f32 v31, v24, v25
	v_add_u32_e32 v36, 0xa0, v168
	v_mad_u64_u32 v[24:25], s[18:19], v36, s11, v[120:121]
	v_cvt_pk_bf16_f32 v4, v4, v5
	v_cvt_pk_bf16_f32 v5, v6, v7
	v_lshlrev_b32_e32 v6, 16, v66
	v_and_b32_e32 v7, 0xffff0000, v66
	v_lshl_add_u64 v[24:25], v[24:25], 0, v[122:123]
	v_pk_mul_f32 v[0:1], v[0:1], v[6:7]
	flat_store_dwordx4 v[24:25], v[20:23] offset:3328 nt
	v_cvt_pk_bf16_f32 v6, v0, v1
	v_lshlrev_b32_e32 v0, 16, v67
	v_add_u32_e32 v20, 0xb0, v168
	v_and_b32_e32 v1, 0xffff0000, v67
	v_cvt_pk_bf16_f32 v15, v8, v9
	v_mad_u64_u32 v[8:9], s[18:19], v20, s11, v[120:121]
	v_pk_mul_f32 v[0:1], v[2:3], v[0:1]
	v_lshl_add_u64 v[8:9], v[8:9], 0, v[122:123]
	v_cvt_pk_bf16_f32 v7, v0, v1
	s_mov_b64 s[18:19], -1
	flat_store_dwordx4 v[56:57], v[60:63] offset:3072 nt
	flat_store_dwordx4 v[40:41], v[44:47] offset:3072 nt
	flat_store_dwordx4 v[24:25], v[28:31] offset:3072 nt
	flat_store_dwordx4 v[8:9], v[12:15] offset:3072 nt
	flat_store_dwordx4 v[8:9], v[4:7] offset:3328 nt
	s_cbranch_vccnz .LBB0_646
	s_andn2_b64 vcc, exec, s[4:5]
	s_cbranch_vccnz .LBB0_645
	s_barrier
	s_branch .LBB0_645

.LBB0_673:
	s_lshl_b32 s9, s22, 12
	s_lshl_b32 s13, s18, 8
	v_mov_b32_e32 v128, v168
	v_mov_b32_e32 v129, v169
	s_addk_i32 s9, 0x2000
	s_or_b32 s13, s13, s43
	s_lshl_b32 s11, s20, 8
	v_lshl_add_u32 v192, v129, 3, s13
	s_ashr_i32 s13, s9, 8
	s_add_i32 s13, s13, s20
	s_mul_hi_i32 s19, s13, 0x280000
	s_mul_i32 s13, s13, 0x280000
	s_add_u32 s13, s39, s13
	s_addc_u32 s20, s40, s19
	s_ashr_i32 s19, s18, 31
	s_lshl_b64 s[18:19], s[18:19], 17
	s_add_u32 s18, s13, s18
	s_addc_u32 s19, s20, s19
	v_lshlrev_b32_e32 v130, 3, v128
	s_add_i32 s9, s9, s42
	v_lshl_add_u32 v173, v129, 7, v130
	s_add_i32 s9, s9, s11
	v_add_u32_e32 v172, s9, v128
	v_add_u32_e32 v128, s46, v173
	v_mov_b32_e32 v129, v193
	v_lshl_add_u64 v[128:129], v[128:129], 1, s[18:19]
	flat_load_dwordx4 v[174:177], v[128:129]
	v_add_u32_e32 v128, s47, v173
	v_mov_b32_e32 v129, v193
	v_lshl_add_u64 v[128:129], v[128:129], 1, s[18:19]
	flat_load_dwordx4 v[152:155], v[128:129]
	v_add_u32_e32 v128, s48, v173
	v_mov_b32_e32 v129, v193
	v_lshl_add_u64 v[128:129], v[128:129], 1, s[18:19]
	flat_load_dwordx4 v[148:151], v[128:129]
	v_add_u32_e32 v128, s49, v173
	v_mov_b32_e32 v129, v193
	v_lshl_add_u64 v[128:129], v[128:129], 1, s[18:19]
	flat_load_dwordx4 v[144:147], v[128:129]
	v_add_u32_e32 v128, s50, v173
	v_mov_b32_e32 v129, v193
	v_lshl_add_u64 v[128:129], v[128:129], 1, s[18:19]
	flat_load_dwordx4 v[140:143], v[128:129]
	v_add_u32_e32 v128, s51, v173
	v_mov_b32_e32 v129, v193
	v_lshl_add_u64 v[128:129], v[128:129], 1, s[18:19]
	flat_load_dwordx4 v[136:139], v[128:129]
	v_add_u32_e32 v128, s52, v173
	v_mov_b32_e32 v129, v193
	v_lshl_add_u64 v[128:129], v[128:129], 1, s[18:19]
	flat_load_dwordx4 v[132:135], v[128:129]
	v_add_u32_e32 v128, s53, v173
	v_mov_b32_e32 v129, v193
	v_lshl_add_u64 v[128:129], v[128:129], 1, s[18:19]
	flat_load_dwordx4 v[128:131], v[128:129]
	s_movk_i32 s9, 0x1400
	s_and_b64 vcc, exec, s[6:7]
	s_waitcnt vmcnt(0) lgkmcnt(0)
	v_lshlrev_b32_e32 v178, 16, v174
	v_and_b32_e32 v179, 0xffff0000, v174
	v_lshlrev_b32_e32 v174, 16, v175
	v_and_b32_e32 v175, 0xffff0000, v175
	v_pk_mul_f32 v[124:125], v[124:125], v[178:179]
	v_pk_mul_f32 v[126:127], v[126:127], v[174:175]
	v_cvt_pk_bf16_f32 v124, v124, v125
	v_cvt_pk_bf16_f32 v125, v126, v127
	v_lshlrev_b32_e32 v126, 16, v176
	v_and_b32_e32 v127, 0xffff0000, v176
	v_pk_mul_f32 v[120:121], v[120:121], v[126:127]
	s_nop 0
	v_cvt_pk_bf16_f32 v126, v120, v121
	v_lshlrev_b32_e32 v120, 16, v177
	v_and_b32_e32 v121, 0xffff0000, v177
	v_pk_mul_f32 v[120:121], v[122:123], v[120:121]
	v_lshlrev_b64 v[122:123], 1, v[192:193]
	v_cvt_pk_bf16_f32 v127, v120, v121
	v_mov_b64_e32 v[120:121], s[0:1]
	v_mad_u64_u32 v[174:175], s[24:25], v172, s9, v[120:121]
	v_lshl_add_u64 v[174:175], v[174:175], 0, v[122:123]
	flat_store_dwordx4 v[174:175], v[124:127] offset:3072 nt
	v_add_u32_e32 v192, s54, v173
	s_nop 0
	v_lshlrev_b32_e32 v124, 16, v152
	v_and_b32_e32 v125, 0xffff0000, v152
	v_pk_mul_f32 v[116:117], v[116:117], v[124:125]
	v_lshlrev_b32_e32 v124, 16, v153
	v_and_b32_e32 v125, 0xffff0000, v153
	v_pk_mul_f32 v[118:119], v[118:119], v[124:125]
	v_cvt_pk_bf16_f32 v116, v116, v117
	v_cvt_pk_bf16_f32 v117, v118, v119
	v_lshlrev_b32_e32 v118, 16, v154
	v_and_b32_e32 v119, 0xffff0000, v154
	v_pk_mul_f32 v[112:113], v[112:113], v[118:119]
	s_nop 0
	v_cvt_pk_bf16_f32 v118, v112, v113
	v_lshlrev_b32_e32 v112, 16, v155
	v_and_b32_e32 v113, 0xffff0000, v155
	v_pk_mul_f32 v[112:113], v[114:115], v[112:113]
	v_add_u32_e32 v114, 16, v172
	v_cvt_pk_bf16_f32 v119, v112, v113
	v_lshlrev_b32_e32 v112, 16, v148
	v_and_b32_e32 v113, 0xffff0000, v148
	v_pk_mul_f32 v[108:109], v[108:109], v[112:113]
	v_lshlrev_b32_e32 v112, 16, v149
	v_and_b32_e32 v113, 0xffff0000, v149
	v_pk_mul_f32 v[110:111], v[110:111], v[112:113]
	v_cvt_pk_bf16_f32 v108, v108, v109
	v_cvt_pk_bf16_f32 v109, v110, v111
	v_lshlrev_b32_e32 v110, 16, v150
	v_and_b32_e32 v111, 0xffff0000, v150
	v_pk_mul_f32 v[104:105], v[104:105], v[110:111]
	flat_store_dwordx4 v[174:175], v[116:119] offset:3328 nt
	v_cvt_pk_bf16_f32 v110, v104, v105
	v_lshlrev_b32_e32 v104, 16, v151
	v_and_b32_e32 v105, 0xffff0000, v151
	v_pk_mul_f32 v[104:105], v[106:107], v[104:105]
	v_lshlrev_b32_e32 v106, 16, v144
	v_and_b32_e32 v107, 0xffff0000, v144
	v_pk_mul_f32 v[100:101], v[100:101], v[106:107]
	v_lshlrev_b32_e32 v106, 16, v145
	v_and_b32_e32 v107, 0xffff0000, v145
	v_pk_mul_f32 v[102:103], v[102:103], v[106:107]
	v_cvt_pk_bf16_f32 v100, v100, v101
	v_cvt_pk_bf16_f32 v101, v102, v103
	v_lshlrev_b32_e32 v102, 16, v146
	v_and_b32_e32 v103, 0xffff0000, v146
	v_pk_mul_f32 v[92:93], v[92:93], v[102:103]
	v_cvt_pk_bf16_f32 v111, v104, v105
	v_cvt_pk_bf16_f32 v102, v92, v93
	v_lshlrev_b32_e32 v92, 16, v147
	v_and_b32_e32 v93, 0xffff0000, v147
	v_pk_mul_f32 v[92:93], v[94:95], v[92:93]
	v_lshlrev_b32_e32 v94, 16, v141
	v_cvt_pk_bf16_f32 v103, v92, v93
	v_lshlrev_b32_e32 v92, 16, v140
	v_and_b32_e32 v93, 0xffff0000, v140
	v_and_b32_e32 v95, 0xffff0000, v141
	v_pk_mul_f32 v[92:93], v[96:97], v[92:93]
	v_pk_mul_f32 v[94:95], v[98:99], v[94:95]
	v_cvt_pk_bf16_f32 v92, v92, v93
	v_cvt_pk_bf16_f32 v93, v94, v95
	v_lshlrev_b32_e32 v94, 16, v142
	v_and_b32_e32 v95, 0xffff0000, v142
	v_pk_mul_f32 v[88:89], v[88:89], v[94:95]
	v_mad_u64_u32 v[104:105], s[24:25], v114, s9, v[120:121]
	v_cvt_pk_bf16_f32 v94, v88, v89
	v_lshlrev_b32_e32 v88, 16, v143
	v_and_b32_e32 v89, 0xffff0000, v143
	v_pk_mul_f32 v[88:89], v[90:91], v[88:89]
	v_lshlrev_b32_e32 v90, 16, v136
	v_and_b32_e32 v91, 0xffff0000, v136
	v_pk_mul_f32 v[84:85], v[84:85], v[90:91]
	v_lshlrev_b32_e32 v90, 16, v137
	v_and_b32_e32 v91, 0xffff0000, v137
	v_pk_mul_f32 v[86:87], v[86:87], v[90:91]
	v_cvt_pk_bf16_f32 v84, v84, v85
	v_cvt_pk_bf16_f32 v85, v86, v87
	v_lshlrev_b32_e32 v86, 16, v138
	v_and_b32_e32 v87, 0xffff0000, v138
	v_pk_mul_f32 v[76:77], v[76:77], v[86:87]
	v_lshl_add_u64 v[104:105], v[104:105], 0, v[122:123]
	v_cvt_pk_bf16_f32 v86, v76, v77
	v_lshlrev_b32_e32 v76, 16, v139
	v_and_b32_e32 v77, 0xffff0000, v139
	v_pk_mul_f32 v[76:77], v[78:79], v[76:77]
	v_lshlrev_b32_e32 v78, 16, v133
	v_cvt_pk_bf16_f32 v87, v76, v77
	v_lshlrev_b32_e32 v76, 16, v132
	v_and_b32_e32 v77, 0xffff0000, v132
	v_and_b32_e32 v79, 0xffff0000, v133
	v_pk_mul_f32 v[76:77], v[80:81], v[76:77]
	v_pk_mul_f32 v[78:79], v[82:83], v[78:79]
	v_cvt_pk_bf16_f32 v76, v76, v77
	v_cvt_pk_bf16_f32 v77, v78, v79
	v_lshlrev_b32_e32 v78, 16, v134
	v_and_b32_e32 v79, 0xffff0000, v134
	v_pk_mul_f32 v[72:73], v[72:73], v[78:79]
	flat_store_dwordx4 v[104:105], v[100:103] offset:3328 nt
	v_cvt_pk_bf16_f32 v78, v72, v73
	v_lshlrev_b32_e32 v72, 16, v135
	v_and_b32_e32 v73, 0xffff0000, v135
	v_pk_mul_f32 v[72:73], v[74:75], v[72:73]
	v_lshlrev_b32_e32 v74, 16, v128
	v_and_b32_e32 v75, 0xffff0000, v128
	v_pk_mul_f32 v[68:69], v[68:69], v[74:75]
	v_lshlrev_b32_e32 v74, 16, v129
	v_and_b32_e32 v75, 0xffff0000, v129
	v_add_u32_e32 v100, 32, v172
	v_pk_mul_f32 v[70:71], v[70:71], v[74:75]
	v_cvt_pk_bf16_f32 v95, v88, v89
	v_mad_u64_u32 v[88:89], s[24:25], v100, s9, v[120:121]
	v_cvt_pk_bf16_f32 v68, v68, v69
	v_cvt_pk_bf16_f32 v69, v70, v71
	v_lshlrev_b32_e32 v70, 16, v130
	v_and_b32_e32 v71, 0xffff0000, v130
	v_lshl_add_u64 v[88:89], v[88:89], 0, v[122:123]
	v_pk_mul_f32 v[64:65], v[64:65], v[70:71]
	flat_store_dwordx4 v[88:89], v[84:87] offset:3328 nt
	v_cvt_pk_bf16_f32 v70, v64, v65
	v_lshlrev_b32_e32 v64, 16, v131
	v_add_u32_e32 v84, 48, v172
	v_and_b32_e32 v65, 0xffff0000, v131
	v_cvt_pk_bf16_f32 v79, v72, v73
	v_mad_u64_u32 v[72:73], s[24:25], v84, s9, v[120:121]
	v_pk_mul_f32 v[64:65], v[66:67], v[64:65]
	v_lshl_add_u64 v[72:73], v[72:73], 0, v[122:123]
	v_cvt_pk_bf16_f32 v71, v64, v65
	flat_store_dwordx4 v[104:105], v[108:111] offset:3072 nt
	flat_store_dwordx4 v[88:89], v[92:95] offset:3072 nt
	flat_store_dwordx4 v[72:73], v[76:79] offset:3072 nt
	flat_store_dwordx4 v[72:73], v[68:71] offset:3328 nt
	v_lshl_add_u64 v[64:65], v[192:193], 1, s[18:19]
	flat_load_dwordx4 v[68:71], v[64:65]
	v_add_u32_e32 v192, s55, v173
	v_lshl_add_u64 v[64:65], v[192:193], 1, s[18:19]
	flat_load_dwordx4 v[72:75], v[64:65]
	v_add_u32_e32 v192, s56, v173
	v_lshl_add_u64 v[64:65], v[192:193], 1, s[18:19]
	flat_load_dwordx4 v[76:79], v[64:65]
	v_add_u32_e32 v192, s57, v173
	v_lshl_add_u64 v[64:65], v[192:193], 1, s[18:19]
	flat_load_dwordx4 v[80:83], v[64:65]
	v_add_u32_e32 v192, s58, v173
	v_lshl_add_u64 v[64:65], v[192:193], 1, s[18:19]
	flat_load_dwordx4 v[84:87], v[64:65]
	v_add_u32_e32 v192, s59, v173
	v_lshl_add_u64 v[64:65], v[192:193], 1, s[18:19]
	flat_load_dwordx4 v[88:91], v[64:65]
	v_add_u32_e32 v192, s60, v173
	v_lshl_add_u64 v[64:65], v[192:193], 1, s[18:19]
	flat_load_dwordx4 v[92:95], v[64:65]
	v_add_u32_e32 v192, s61, v173
	v_lshl_add_u64 v[64:65], v[192:193], 1, s[18:19]
	flat_load_dwordx4 v[64:67], v[64:65]
	v_add_u32_e32 v98, 0x80, v172
	s_waitcnt vmcnt(0) lgkmcnt(0)
	v_lshlrev_b32_e32 v96, 16, v68
	v_and_b32_e32 v97, 0xffff0000, v68
	v_lshlrev_b32_e32 v68, 16, v69
	v_and_b32_e32 v69, 0xffff0000, v69
	v_pk_mul_f32 v[60:61], v[60:61], v[96:97]
	v_pk_mul_f32 v[62:63], v[62:63], v[68:69]
	v_cvt_pk_bf16_f32 v60, v60, v61
	v_cvt_pk_bf16_f32 v61, v62, v63
	v_lshlrev_b32_e32 v62, 16, v70
	v_and_b32_e32 v63, 0xffff0000, v70
	v_pk_mul_f32 v[56:57], v[56:57], v[62:63]
	s_nop 0
	v_cvt_pk_bf16_f32 v62, v56, v57
	v_lshlrev_b32_e32 v56, 16, v71
	v_and_b32_e32 v57, 0xffff0000, v71
	v_pk_mul_f32 v[56:57], v[58:59], v[56:57]
	v_lshlrev_b32_e32 v58, 16, v72
	v_and_b32_e32 v59, 0xffff0000, v72
	v_pk_mul_f32 v[52:53], v[52:53], v[58:59]
	v_lshlrev_b32_e32 v58, 16, v73
	v_and_b32_e32 v59, 0xffff0000, v73
	v_pk_mul_f32 v[54:55], v[54:55], v[58:59]
	v_cvt_pk_bf16_f32 v52, v52, v53
	v_cvt_pk_bf16_f32 v53, v54, v55
	v_lshlrev_b32_e32 v54, 16, v74
	v_and_b32_e32 v55, 0xffff0000, v74
	v_pk_mul_f32 v[44:45], v[44:45], v[54:55]
	v_cvt_pk_bf16_f32 v63, v56, v57
	v_cvt_pk_bf16_f32 v54, v44, v45
	v_lshlrev_b32_e32 v44, 16, v75
	v_and_b32_e32 v45, 0xffff0000, v75
	v_pk_mul_f32 v[44:45], v[46:47], v[44:45]
	v_lshlrev_b32_e32 v46, 16, v77
	v_cvt_pk_bf16_f32 v55, v44, v45
	v_lshlrev_b32_e32 v44, 16, v76
	v_and_b32_e32 v45, 0xffff0000, v76
	v_and_b32_e32 v47, 0xffff0000, v77
	v_pk_mul_f32 v[44:45], v[48:49], v[44:45]
	v_pk_mul_f32 v[46:47], v[50:51], v[46:47]
	v_cvt_pk_bf16_f32 v44, v44, v45
	v_cvt_pk_bf16_f32 v45, v46, v47
	v_lshlrev_b32_e32 v46, 16, v78
	v_and_b32_e32 v47, 0xffff0000, v78
	v_pk_mul_f32 v[40:41], v[40:41], v[46:47]
	v_mad_u64_u32 v[56:57], s[18:19], v98, s9, v[120:121]
	v_cvt_pk_bf16_f32 v46, v40, v41
	v_lshlrev_b32_e32 v40, 16, v79
	v_and_b32_e32 v41, 0xffff0000, v79
	v_pk_mul_f32 v[40:41], v[42:43], v[40:41]
	v_lshlrev_b32_e32 v42, 16, v80
	v_and_b32_e32 v43, 0xffff0000, v80
	v_pk_mul_f32 v[36:37], v[36:37], v[42:43]
	v_lshlrev_b32_e32 v42, 16, v81
	v_and_b32_e32 v43, 0xffff0000, v81
	v_pk_mul_f32 v[38:39], v[38:39], v[42:43]
	v_cvt_pk_bf16_f32 v36, v36, v37
	v_cvt_pk_bf16_f32 v37, v38, v39
	v_lshlrev_b32_e32 v38, 16, v82
	v_and_b32_e32 v39, 0xffff0000, v82
	v_pk_mul_f32 v[28:29], v[28:29], v[38:39]
	v_lshl_add_u64 v[56:57], v[56:57], 0, v[122:123]
	v_cvt_pk_bf16_f32 v38, v28, v29
	v_lshlrev_b32_e32 v28, 16, v83
	v_and_b32_e32 v29, 0xffff0000, v83
	v_pk_mul_f32 v[28:29], v[30:31], v[28:29]
	v_lshlrev_b32_e32 v30, 16, v85
	v_cvt_pk_bf16_f32 v39, v28, v29
	v_lshlrev_b32_e32 v28, 16, v84
	v_and_b32_e32 v29, 0xffff0000, v84
	v_and_b32_e32 v31, 0xffff0000, v85
	v_pk_mul_f32 v[28:29], v[32:33], v[28:29]
	v_pk_mul_f32 v[30:31], v[34:35], v[30:31]
	v_cvt_pk_bf16_f32 v28, v28, v29
	v_cvt_pk_bf16_f32 v29, v30, v31
	v_lshlrev_b32_e32 v30, 16, v86
	v_and_b32_e32 v31, 0xffff0000, v86
	v_pk_mul_f32 v[24:25], v[24:25], v[30:31]
	flat_store_dwordx4 v[56:57], v[52:55] offset:3328 nt
	v_cvt_pk_bf16_f32 v30, v24, v25
	v_lshlrev_b32_e32 v24, 16, v87
	v_and_b32_e32 v25, 0xffff0000, v87
	v_pk_mul_f32 v[24:25], v[26:27], v[24:25]
	v_lshlrev_b32_e32 v26, 16, v88
	v_and_b32_e32 v27, 0xffff0000, v88
	v_pk_mul_f32 v[20:21], v[20:21], v[26:27]
	v_lshlrev_b32_e32 v26, 16, v89
	v_and_b32_e32 v27, 0xffff0000, v89
	v_pk_mul_f32 v[22:23], v[22:23], v[26:27]
	v_cvt_pk_bf16_f32 v20, v20, v21
	v_cvt_pk_bf16_f32 v21, v22, v23
	v_lshlrev_b32_e32 v22, 16, v90
	v_and_b32_e32 v23, 0xffff0000, v90
	v_pk_mul_f32 v[12:13], v[12:13], v[22:23]
	v_add_u32_e32 v52, 0x90, v172
	v_cvt_pk_bf16_f32 v22, v12, v13
	v_lshlrev_b32_e32 v12, 16, v91
	v_and_b32_e32 v13, 0xffff0000, v91
	v_pk_mul_f32 v[12:13], v[14:15], v[12:13]
	v_lshlrev_b32_e32 v14, 16, v93
	v_cvt_pk_bf16_f32 v23, v12, v13
	v_lshlrev_b32_e32 v12, 16, v92
	v_and_b32_e32 v13, 0xffff0000, v92
	v_and_b32_e32 v15, 0xffff0000, v93
	v_pk_mul_f32 v[12:13], v[16:17], v[12:13]
	v_pk_mul_f32 v[14:15], v[18:19], v[14:15]
	v_cvt_pk_bf16_f32 v12, v12, v13
	v_cvt_pk_bf16_f32 v13, v14, v15
	v_lshlrev_b32_e32 v14, 16, v94
	v_and_b32_e32 v15, 0xffff0000, v94
	v_pk_mul_f32 v[8:9], v[8:9], v[14:15]
	v_cvt_pk_bf16_f32 v47, v40, v41
	v_cvt_pk_bf16_f32 v14, v8, v9
	v_lshlrev_b32_e32 v8, 16, v95
	v_and_b32_e32 v9, 0xffff0000, v95
	v_mad_u64_u32 v[40:41], s[18:19], v52, s9, v[120:121]
	v_pk_mul_f32 v[8:9], v[10:11], v[8:9]
	v_lshlrev_b32_e32 v10, 16, v64
	v_and_b32_e32 v11, 0xffff0000, v64
	v_lshl_add_u64 v[40:41], v[40:41], 0, v[122:123]
	v_pk_mul_f32 v[4:5], v[4:5], v[10:11]
	v_lshlrev_b32_e32 v10, 16, v65
	v_and_b32_e32 v11, 0xffff0000, v65
	flat_store_dwordx4 v[40:41], v[36:39] offset:3328 nt
	v_pk_mul_f32 v[6:7], v[6:7], v[10:11]
	v_cvt_pk_bf16_f32 v31, v24, v25
	v_add_u32_e32 v36, 0xa0, v172
	v_mad_u64_u32 v[24:25], s[18:19], v36, s9, v[120:121]
	v_cvt_pk_bf16_f32 v4, v4, v5
	v_cvt_pk_bf16_f32 v5, v6, v7
	v_lshlrev_b32_e32 v6, 16, v66
	v_and_b32_e32 v7, 0xffff0000, v66
	v_lshl_add_u64 v[24:25], v[24:25], 0, v[122:123]
	v_pk_mul_f32 v[0:1], v[0:1], v[6:7]
	flat_store_dwordx4 v[24:25], v[20:23] offset:3328 nt
	v_cvt_pk_bf16_f32 v6, v0, v1
	v_lshlrev_b32_e32 v0, 16, v67
	v_add_u32_e32 v20, 0xb0, v172
	v_and_b32_e32 v1, 0xffff0000, v67
	v_cvt_pk_bf16_f32 v15, v8, v9
	v_mad_u64_u32 v[8:9], s[18:19], v20, s9, v[120:121]
	v_pk_mul_f32 v[0:1], v[2:3], v[0:1]
	v_lshl_add_u64 v[8:9], v[8:9], 0, v[122:123]
	v_cvt_pk_bf16_f32 v7, v0, v1
	s_mov_b64 s[18:19], -1
	flat_store_dwordx4 v[56:57], v[60:63] offset:3072 nt
	flat_store_dwordx4 v[40:41], v[44:47] offset:3072 nt
	flat_store_dwordx4 v[24:25], v[28:31] offset:3072 nt
	flat_store_dwordx4 v[8:9], v[12:15] offset:3072 nt
	flat_store_dwordx4 v[8:9], v[4:7] offset:3328 nt
	s_cbranch_vccnz .LBB0_664
	s_andn2_b64 vcc, exec, s[2:3]
	s_cbranch_vccnz .LBB0_663
	s_barrier
	s_branch .LBB0_663
